# nt policy additionally on read-once loads in P0/P5/P7 and GEMM epilogue residual loads
# baseline (speedup 1.0000x reference)
.LBB0_23:
	s_cmpk_gt_i32 s56, 0x7f
	s_mov_b64 s[6:7], -1
	s_cbranch_scc0 .LBB0_57
	s_and_saveexec_b64 s[6:7], s[36:37]
	s_xor_b64 s[6:7], exec, s[6:7]
	s_cbranch_execz .LBB0_26
	global_load_dwordx4 v[2:5], v[28:29], off nt
	global_load_dwordx4 v[30:33], v[22:23], off nt
	s_waitcnt vmcnt(1)
	ds_write_b128 v64, v[2:5] offset:14848
	s_waitcnt vmcnt(0)
	ds_write_b128 v64, v[30:33] offset:23040

.LBB0_28:
	v_ashrrev_i32_e32 v3, 31, v2
	v_lshl_add_u64 v[30:31], v[2:3], 2, s[42:43]
	global_load_dwordx4 v[30:33], v[30:31], off nt
	v_add_u32_e32 v5, 0x200, v5
	s_movk_i32 s4, 0xff0f
	v_cmp_lt_i32_e32 vcc, s4, v5
	v_add_u32_e32 v2, 0x800, v2
	s_or_b64 s[12:13], vcc, s[12:13]
	s_waitcnt vmcnt(0)
	ds_write_b128 v4, v[30:33]
	v_add_u32_e32 v4, 0x2000, v4
	s_andn2_b64 exec, exec, s[12:13]
	s_cbranch_execnz .LBB0_28
	s_or_b64 exec, exec, s[12:13]
	global_load_dwordx4 v[30:33], v[28:29], off nt
	global_load_dwordx4 v[38:41], v[22:23], off nt
	v_lshl_add_u32 v2, s3, 4, v65
	v_cvt_f32_i32_e32 v3, v2
	s_waitcnt vmcnt(1)
	ds_write_b128 v64, v[30:33] offset:14848
	s_waitcnt vmcnt(0)
	ds_write_b128 v64, v[38:41] offset:23040
	s_and_saveexec_b64 s[12:13], s[38:39]
	s_xor_b64 s[12:13], exec, s[12:13]
	s_cbranch_execz .LBB0_35
	v_mul_f32_e32 v2, 0x40c90fdb, v3
	v_mul_f32_e32 v2, 0x3a000000, v2
	v_mul_f32_e32 v3, v86, v2
	s_and_saveexec_b64 s[50:51], s[40:41]
	s_xor_b64 s[50:51], exec, s[50:51]
	v_mul_f32_e32 v2, 0xbe22f983, v3
	v_sin_f32_e32 v2, v2
	s_andn2_saveexec_b64 s[50:51], s[50:51]
	v_mul_f32_e32 v2, 0.15915494, v3
	v_cos_f32_e32 v2, v2
	s_or_b64 exec, exec, s[50:51]

.LBB0_57:
	s_and_b64 vcc, exec, s[6:7]
	s_cbranch_vccz .LBB0_22
	s_lshl_b32 s4, s56, 2
	s_and_b32 s6, s4, 0xffffff80
	s_lshl_b32 s3, s56, 6
	s_ashr_i32 s7, s6, 31
	s_and_b32 s3, s3, 0x7c0
	s_lshl_b64 s[12:13], s[6:7], 2
	s_add_u32 s12, s22, s12
	s_addc_u32 s13, s23, s13
	v_add_u32_e32 v30, s3, v37
	v_mov_b64_e32 v[32:33], s[12:13]
	v_ashrrev_i32_e32 v31, 31, v30
	v_mad_i64_i32 v[2:3], s[12:13], v30, s62, v[32:33]
	v_lshl_add_u64 v[2:3], v[2:3], 0, v[114:115]
	v_lshl_add_u64 v[30:31], v[30:31], 2, s[24:25]
	global_load_dwordx4 v[2:5], v[2:3], off nt
	v_mov_b32_e32 v46, 0
	global_load_dword v30, v[30:31], off
	s_mov_b32 s4, -4
	v_mov_b32_e32 v93, v88
	v_mov_b32_e32 v94, v92
	v_mov_b32_e32 v47, v46
	v_mov_b32_e32 v40, v46
	v_mov_b32_e32 v38, v46
	v_mov_b32_e32 v41, v46
	v_mov_b32_e32 v39, v46
	v_mov_b32_e32 v44, v46
	v_mov_b32_e32 v42, v46
	v_mov_b32_e32 v45, v46
	v_mov_b32_e32 v43, v46
	v_mov_b32_e32 v48, v46
	v_mov_b32_e32 v49, v46
	s_waitcnt vmcnt(0)
	v_pk_mul_f32 v[2:3], v[2:3], v[30:31] op_sel_hi:[1,0]
	v_pk_mul_f32 v[4:5], v[4:5], v[30:31] op_sel_hi:[1,0]
	v_add_u32_e32 v30, s3, v68
	ds_write_b128 v76, v[2:5]
	v_ashrrev_i32_e32 v31, 31, v30
	v_mad_i64_i32 v[2:3], s[12:13], v30, s62, v[32:33]
	v_lshl_add_u64 v[2:3], v[2:3], 0, v[114:115]
	v_lshl_add_u64 v[30:31], v[30:31], 2, s[24:25]
	global_load_dwordx4 v[2:5], v[2:3], off nt
	s_nop 0
	global_load_dword v30, v[30:31], off
	s_waitcnt vmcnt(0)
	v_pk_mul_f32 v[2:3], v[2:3], v[30:31] op_sel_hi:[1,0]
	v_pk_mul_f32 v[4:5], v[4:5], v[30:31] op_sel_hi:[1,0]
	v_add_u32_e32 v30, s3, v69
	ds_write_b128 v77, v[2:5]
	v_ashrrev_i32_e32 v31, 31, v30
	v_mad_i64_i32 v[2:3], s[12:13], v30, s62, v[32:33]
	v_lshl_add_u64 v[2:3], v[2:3], 0, v[114:115]
	v_lshl_add_u64 v[30:31], v[30:31], 2, s[24:25]
	global_load_dwordx4 v[2:5], v[2:3], off nt
	s_nop 0
	global_load_dword v30, v[30:31], off
	s_waitcnt vmcnt(0)
	v_pk_mul_f32 v[2:3], v[2:3], v[30:31] op_sel_hi:[1,0]
	v_pk_mul_f32 v[4:5], v[4:5], v[30:31] op_sel_hi:[1,0]
	v_add_u32_e32 v30, s3, v70
	ds_write_b128 v78, v[2:5]
	v_ashrrev_i32_e32 v31, 31, v30
	v_mad_i64_i32 v[2:3], s[12:13], v30, s62, v[32:33]
	v_lshl_add_u64 v[2:3], v[2:3], 0, v[114:115]
	v_lshl_add_u64 v[30:31], v[30:31], 2, s[24:25]
	global_load_dwordx4 v[2:5], v[2:3], off nt
	v_mov_b32_e32 v32, v46
	global_load_dword v30, v[30:31], off
	v_mov_b32_e32 v33, v46
	s_waitcnt vmcnt(0)
	v_pk_mul_f32 v[2:3], v[2:3], v[30:31] op_sel_hi:[1,0]
	v_pk_mul_f32 v[4:5], v[4:5], v[30:31] op_sel_hi:[1,0]
	ds_write_b128 v79, v[2:5]
	v_add_u32_e32 v2, s6, v37
	v_ashrrev_i32_e32 v3, 31, v2
	v_lshlrev_b64 v[2:3], 9, v[2:3]
	v_lshl_add_u64 v[2:3], v[14:15], 0, v[2:3]
	global_load_dwordx4 v[2:5], v[2:3], off nt
	v_mov_b32_e32 v30, v46
	v_mov_b32_e32 v31, v46
	s_waitcnt vmcnt(0)
	ds_write_b128 v76, v[2:5] offset:32768
	v_add_u32_e32 v2, s6, v68
	v_ashrrev_i32_e32 v3, 31, v2
	v_lshlrev_b64 v[2:3], 9, v[2:3]
	v_lshl_add_u64 v[2:3], v[14:15], 0, v[2:3]
	global_load_dwordx4 v[2:5], v[2:3], off nt
	s_waitcnt vmcnt(0)
	ds_write_b128 v77, v[2:5] offset:32768
	v_add_u32_e32 v2, s6, v69
	v_ashrrev_i32_e32 v3, 31, v2
	v_lshlrev_b64 v[2:3], 9, v[2:3]
	v_lshl_add_u64 v[2:3], v[14:15], 0, v[2:3]
	global_load_dwordx4 v[2:5], v[2:3], off nt
	s_waitcnt vmcnt(0)
	ds_write_b128 v78, v[2:5] offset:32768
	v_add_u32_e32 v2, s6, v70
	v_ashrrev_i32_e32 v3, 31, v2
	v_lshlrev_b64 v[2:3], 9, v[2:3]
	v_lshl_add_u64 v[2:3], v[14:15], 0, v[2:3]
	global_load_dwordx4 v[2:5], v[2:3], off nt
	s_waitcnt vmcnt(0)
	ds_write_b128 v79, v[2:5] offset:32768
	v_add_u32_e32 v2, s6, v71
	v_ashrrev_i32_e32 v3, 31, v2
	v_lshlrev_b64 v[2:3], 9, v[2:3]
	v_lshl_add_u64 v[2:3], v[14:15], 0, v[2:3]
	global_load_dwordx4 v[2:5], v[2:3], off nt
	s_waitcnt vmcnt(0)
	ds_write_b128 v80, v[2:5] offset:32768
	v_add_u32_e32 v2, s6, v72
	v_ashrrev_i32_e32 v3, 31, v2
	v_lshlrev_b64 v[2:3], 9, v[2:3]
	v_lshl_add_u64 v[2:3], v[14:15], 0, v[2:3]
	global_load_dwordx4 v[2:5], v[2:3], off nt
	s_waitcnt vmcnt(0)
	ds_write_b128 v81, v[2:5] offset:32768
	v_add_u32_e32 v2, s6, v73
	v_ashrrev_i32_e32 v3, 31, v2
	v_lshlrev_b64 v[2:3], 9, v[2:3]
	v_lshl_add_u64 v[2:3], v[14:15], 0, v[2:3]
	global_load_dwordx4 v[2:5], v[2:3], off nt
	s_waitcnt vmcnt(0)
	ds_write_b128 v82, v[2:5] offset:32768
	v_add_u32_e32 v2, s6, v74
	v_ashrrev_i32_e32 v3, 31, v2
	v_lshlrev_b64 v[2:3], 9, v[2:3]
	v_lshl_add_u64 v[2:3], v[14:15], 0, v[2:3]
	global_load_dwordx4 v[2:5], v[2:3], off nt
	s_waitcnt vmcnt(0)
	ds_write_b128 v83, v[2:5] offset:32768
	s_waitcnt lgkmcnt(0)
	s_barrier

.LBB0_75:
	s_and_b32 s4, s1, 0x3f80
	s_and_b32 s12, s3, 0x780
	s_addk_i32 s4, 0xec00
	v_add_u32_e32 v16, s12, v37
	v_lshl_add_u64 v[14:15], s[4:5], 2, v[10:11]
	v_ashrrev_i32_e32 v17, 31, v16
	v_mad_i64_i32 v[2:3], s[40:41], v16, s68, v[14:15]
	v_lshl_add_u64 v[16:17], v[16:17], 2, s[50:51]
	global_load_dwordx4 v[2:5], v[2:3], off nt
	v_add_u32_e32 v42, s12, v7
	global_load_dword v16, v[16:17], off
	v_ashrrev_i32_e32 v43, 31, v42
	s_waitcnt vmcnt(0)
	v_pk_mul_f32 v[40:41], v[4:5], v[16:17] op_sel_hi:[1,0]
	v_pk_mul_f32 v[16:17], v[2:3], v[16:17] op_sel_hi:[1,0]
	v_mad_i64_i32 v[2:3], s[40:41], v42, s68, v[14:15]
	v_lshl_add_u64 v[42:43], v[42:43], 2, s[50:51]
	global_load_dwordx4 v[2:5], v[2:3], off nt
	s_nop 0
	global_load_dword v42, v[42:43], off
	s_waitcnt vmcnt(0)
	v_pk_mul_f32 v[2:3], v[2:3], v[42:43] op_sel_hi:[1,0]
	s_nop 0
	v_max3_f32 v44, |v16|, 0, |v2|
	v_add_u32_e32 v16, s12, v9
	v_max3_f32 v45, |v17|, 0, |v3|
	v_ashrrev_i32_e32 v17, 31, v16
	v_pk_mul_f32 v[4:5], v[4:5], v[42:43] op_sel_hi:[1,0]
	v_mad_i64_i32 v[2:3], s[40:41], v16, s68, v[14:15]
	v_lshl_add_u64 v[16:17], v[16:17], 2, s[50:51]
	v_max3_f32 v46, |v40|, 0, |v4|
	v_max3_f32 v47, |v41|, 0, |v5|
	global_load_dwordx4 v[2:5], v[2:3], off nt
	v_add_u32_e32 v42, s12, v18
	global_load_dword v16, v[16:17], off
	v_ashrrev_i32_e32 v43, 31, v42
	s_waitcnt vmcnt(0)
	v_pk_mul_f32 v[40:41], v[4:5], v[16:17] op_sel_hi:[1,0]
	v_pk_mul_f32 v[16:17], v[2:3], v[16:17] op_sel_hi:[1,0]
	v_mad_i64_i32 v[2:3], s[40:41], v42, s68, v[14:15]
	v_lshl_add_u64 v[42:43], v[42:43], 2, s[50:51]
	global_load_dwordx4 v[2:5], v[2:3], off nt
	s_nop 0
	global_load_dword v42, v[42:43], off
	s_waitcnt vmcnt(0)
	v_pk_mul_f32 v[2:3], v[2:3], v[42:43] op_sel_hi:[1,0]
	s_nop 0
	v_max3_f32 v44, v44, |v16|, |v2|
	v_add_u32_e32 v16, s12, v19
	v_max3_f32 v45, v45, |v17|, |v3|
	v_ashrrev_i32_e32 v17, 31, v16
	v_pk_mul_f32 v[4:5], v[4:5], v[42:43] op_sel_hi:[1,0]
	v_mad_i64_i32 v[2:3], s[40:41], v16, s68, v[14:15]
	v_lshl_add_u64 v[16:17], v[16:17], 2, s[50:51]
	v_max3_f32 v46, v46, |v40|, |v4|
	v_max3_f32 v47, v47, |v41|, |v5|
	global_load_dwordx4 v[2:5], v[2:3], off nt
	v_add_u32_e32 v42, s12, v20
	global_load_dword v16, v[16:17], off
	v_ashrrev_i32_e32 v43, 31, v42
	s_waitcnt vmcnt(0)
	v_pk_mul_f32 v[40:41], v[4:5], v[16:17] op_sel_hi:[1,0]
	v_pk_mul_f32 v[16:17], v[2:3], v[16:17] op_sel_hi:[1,0]
	v_mad_i64_i32 v[2:3], s[40:41], v42, s68, v[14:15]
	v_lshl_add_u64 v[42:43], v[42:43], 2, s[50:51]
	global_load_dwordx4 v[2:5], v[2:3], off nt
	s_nop 0
	global_load_dword v42, v[42:43], off
	s_waitcnt vmcnt(0)
	v_pk_mul_f32 v[2:3], v[2:3], v[42:43] op_sel_hi:[1,0]
	s_nop 0
	v_max3_f32 v44, v44, |v16|, |v2|
	v_add_u32_e32 v16, s12, v21
	v_max3_f32 v45, v45, |v17|, |v3|
	v_ashrrev_i32_e32 v17, 31, v16
	v_pk_mul_f32 v[4:5], v[4:5], v[42:43] op_sel_hi:[1,0]
	v_mad_i64_i32 v[2:3], s[40:41], v16, s68, v[14:15]
	v_lshl_add_u64 v[16:17], v[16:17], 2, s[50:51]
	v_max3_f32 v46, v46, |v40|, |v4|
	v_max3_f32 v47, v47, |v41|, |v5|
	global_load_dwordx4 v[2:5], v[2:3], off nt
	v_add_u32_e32 v42, s12, v22
	global_load_dword v16, v[16:17], off
	v_ashrrev_i32_e32 v43, 31, v42
	s_waitcnt vmcnt(0)
	v_pk_mul_f32 v[40:41], v[4:5], v[16:17] op_sel_hi:[1,0]
	v_pk_mul_f32 v[16:17], v[2:3], v[16:17] op_sel_hi:[1,0]
	v_mad_i64_i32 v[2:3], s[12:13], v42, s68, v[14:15]
	v_lshl_add_u64 v[14:15], v[42:43], 2, s[50:51]
	global_load_dwordx4 v[2:5], v[2:3], off nt
	s_nop 0
	global_load_dword v14, v[14:15], off
	s_waitcnt vmcnt(0)
	v_pk_mul_f32 v[4:5], v[4:5], v[14:15] op_sel_hi:[1,0]
	v_pk_mul_f32 v[2:3], v[2:3], v[14:15] op_sel_hi:[1,0]
	v_max3_f32 v4, v46, |v40|, |v4|
	v_max3_f32 v2, v44, |v16|, |v2|
	v_max3_f32 v3, v45, |v17|, |v3|
	v_max3_f32 v5, v47, |v41|, |v5|
	ds_write_b128 v23, v[2:5]
	s_waitcnt lgkmcnt(0)
	s_barrier
	s_and_saveexec_b64 s[12:13], s[36:37]
	s_cbranch_execz .LBB0_77
	ds_read2st64_b32 v[2:3], v24 offset1:2
	s_waitcnt lgkmcnt(0)
	v_max_f32_e32 v3, v3, v3
	v_max_f32_e32 v2, v2, v2
	v_max_f32_e32 v4, v2, v3
	ds_read2st64_b32 v[2:3], v24 offset0:4 offset1:6
	s_waitcnt lgkmcnt(0)
	v_max3_f32 v4, v4, v2, v3
	ds_read2st64_b32 v[2:3], v24 offset0:8 offset1:10
	s_waitcnt lgkmcnt(0)
	v_max3_f32 v4, v4, v2, v3
	ds_read2st64_b32 v[2:3], v24 offset0:12 offset1:14
	s_waitcnt lgkmcnt(0)
	v_max3_f32 v4, v4, v2, v3
	ds_read2st64_b32 v[2:3], v24 offset0:16 offset1:18
	s_waitcnt lgkmcnt(0)
	v_max3_f32 v4, v4, v2, v3
	ds_read2st64_b32 v[2:3], v24 offset0:20 offset1:22
	s_waitcnt lgkmcnt(0)
	v_max3_f32 v4, v4, v2, v3
	ds_read2st64_b32 v[2:3], v24 offset0:24 offset1:26
	s_waitcnt lgkmcnt(0)
	v_max3_f32 v4, v4, v2, v3
	ds_read2st64_b32 v[2:3], v24 offset0:28 offset1:30
	s_waitcnt lgkmcnt(0)
	v_max3_f32 v4, v4, v2, v3
	v_lshl_add_u64 v[2:3], s[4:5], 2, v[12:13]
	global_atomic_umax v[2:3], v4, off

.LBB0_87:
	s_andn2_b64 vcc, exec, s[38:39]
	s_cbranch_vccnz .LBB0_64
	s_ashr_i32 s83, s82, 31
	s_lshl_b64 s[88:89], s[82:83], 2
	s_add_u32 s40, s40, s88
	s_addc_u32 s41, s41, s89
	v_lshlrev_b32_e32 v114, 2, v8
	v_add_u32_e32 v2, s82, v8
	v_lshl_add_u64 v[14:15], s[40:41], 0, v[114:115]
	v_mov_b32_e32 v114, v115
	v_cmp_gt_i32_e64 s[38:39], s4, v2
	v_mov_b32_e32 v116, v115
	v_mov_b32_e32 v117, v115
	v_add_u32_e32 v16, s80, v37
	v_mov_b64_e32 v[2:3], v[114:115]
	v_ashrrev_i32_e32 v17, 31, v16
	v_mov_b64_e32 v[4:5], v[116:117]
	s_and_saveexec_b64 s[40:41], s[38:39]
	s_cbranch_execz .LBB0_90
	v_mad_u64_u32 v[2:3], s[88:89], v16, s4, 0
	v_mov_b32_e32 v4, v3
	v_mad_u64_u32 v[4:5], s[88:89], v17, s4, v[4:5]
	v_mov_b32_e32 v3, v4
	v_lshl_add_u64 v[2:3], v[2:3], 2, v[14:15]
	global_load_dwordx4 v[2:5], v[2:3], off nt

.LBB0_92:
	v_mov_b32_e32 v114, v115
	s_waitcnt vmcnt(0)
	ds_write2_b32 v28, v2, v3 offset1:1
	ds_write2_b32 v28, v4, v5 offset0:2 offset1:3
	v_mov_b32_e32 v116, v115
	v_mov_b32_e32 v117, v115
	v_add_u32_e32 v16, s80, v7
	v_mov_b64_e32 v[2:3], v[114:115]
	v_ashrrev_i32_e32 v17, 31, v16
	v_mov_b64_e32 v[4:5], v[116:117]
	s_and_saveexec_b64 s[40:41], s[38:39]
	s_cbranch_execz .LBB0_94
	v_mad_u64_u32 v[2:3], s[88:89], v16, s4, 0
	v_mov_b32_e32 v4, v3
	v_mad_u64_u32 v[4:5], s[88:89], v17, s4, v[4:5]
	v_mov_b32_e32 v3, v4
	v_lshl_add_u64 v[2:3], v[2:3], 2, v[14:15]
	global_load_dwordx4 v[2:5], v[2:3], off nt

.LBB0_96:
	v_mov_b32_e32 v114, v115
	s_waitcnt vmcnt(0)
	ds_write2_b32 v29, v2, v3 offset1:1
	ds_write2_b32 v29, v4, v5 offset0:2 offset1:3
	v_mov_b32_e32 v116, v115
	v_mov_b32_e32 v117, v115
	v_add_u32_e32 v16, s80, v9
	v_mov_b64_e32 v[2:3], v[114:115]
	v_ashrrev_i32_e32 v17, 31, v16
	v_mov_b64_e32 v[4:5], v[116:117]
	s_and_saveexec_b64 vcc, s[38:39]
	s_cbranch_execz .LBB0_98
	v_mad_u64_u32 v[2:3], s[88:89], v16, s4, 0
	v_mov_b32_e32 v4, v3
	v_mad_u64_u32 v[4:5], s[88:89], v17, s4, v[4:5]
	v_mov_b32_e32 v3, v4
	v_lshl_add_u64 v[2:3], v[2:3], 2, v[14:15]
	global_load_dwordx4 v[2:5], v[2:3], off nt

.LBB0_100:
	v_mov_b32_e32 v114, v115
	s_waitcnt vmcnt(0)
	ds_write2_b32 v30, v2, v3 offset1:1
	ds_write2_b32 v30, v4, v5 offset0:2 offset1:3
	v_mov_b32_e32 v116, v115
	v_mov_b32_e32 v117, v115
	v_add_u32_e32 v16, s80, v18
	v_mov_b64_e32 v[2:3], v[114:115]
	v_ashrrev_i32_e32 v17, 31, v16
	v_mov_b64_e32 v[4:5], v[116:117]
	s_and_saveexec_b64 vcc, s[38:39]
	s_cbranch_execz .LBB0_102
	v_mad_u64_u32 v[2:3], s[88:89], v16, s4, 0
	v_mov_b32_e32 v4, v3
	v_mad_u64_u32 v[4:5], s[88:89], v17, s4, v[4:5]
	v_mov_b32_e32 v3, v4
	v_lshl_add_u64 v[2:3], v[2:3], 2, v[14:15]
	global_load_dwordx4 v[2:5], v[2:3], off nt

.LBB0_104:
	v_mov_b32_e32 v114, v115
	s_waitcnt vmcnt(0)
	ds_write2_b32 v31, v2, v3 offset1:1
	ds_write2_b32 v31, v4, v5 offset0:2 offset1:3
	v_mov_b32_e32 v116, v115
	v_mov_b32_e32 v117, v115
	v_add_u32_e32 v16, s80, v19
	v_mov_b64_e32 v[2:3], v[114:115]
	v_ashrrev_i32_e32 v17, 31, v16
	v_mov_b64_e32 v[4:5], v[116:117]
	s_and_saveexec_b64 vcc, s[38:39]
	s_cbranch_execz .LBB0_106
	v_mad_u64_u32 v[2:3], s[88:89], v16, s4, 0
	v_mov_b32_e32 v4, v3
	v_mad_u64_u32 v[4:5], s[88:89], v17, s4, v[4:5]
	v_mov_b32_e32 v3, v4
	v_lshl_add_u64 v[2:3], v[2:3], 2, v[14:15]
	global_load_dwordx4 v[2:5], v[2:3], off nt

.LBB0_108:
	v_mov_b32_e32 v114, v115
	s_waitcnt vmcnt(0)
	ds_write2_b32 v32, v2, v3 offset1:1
	ds_write2_b32 v32, v4, v5 offset0:2 offset1:3
	v_mov_b32_e32 v116, v115
	v_mov_b32_e32 v117, v115
	v_add_u32_e32 v16, s80, v20
	v_mov_b64_e32 v[2:3], v[114:115]
	v_ashrrev_i32_e32 v17, 31, v16
	v_mov_b64_e32 v[4:5], v[116:117]
	s_and_saveexec_b64 vcc, s[38:39]
	s_cbranch_execz .LBB0_110
	v_mad_u64_u32 v[2:3], s[88:89], v16, s4, 0
	v_mov_b32_e32 v4, v3
	v_mad_u64_u32 v[4:5], s[88:89], v17, s4, v[4:5]
	v_mov_b32_e32 v3, v4
	v_lshl_add_u64 v[2:3], v[2:3], 2, v[14:15]
	global_load_dwordx4 v[2:5], v[2:3], off nt

.LBB0_112:
	v_mov_b32_e32 v114, v115
	s_waitcnt vmcnt(0)
	ds_write2_b32 v33, v2, v3 offset1:1
	ds_write2_b32 v33, v4, v5 offset0:2 offset1:3
	v_mov_b32_e32 v116, v115
	v_mov_b32_e32 v117, v115
	v_add_u32_e32 v16, s80, v21
	v_mov_b64_e32 v[2:3], v[114:115]
	v_ashrrev_i32_e32 v17, 31, v16
	v_mov_b64_e32 v[4:5], v[116:117]
	s_and_saveexec_b64 vcc, s[38:39]
	s_cbranch_execz .LBB0_114
	v_mad_u64_u32 v[2:3], s[88:89], v16, s4, 0
	v_mov_b32_e32 v4, v3
	v_mad_u64_u32 v[4:5], s[88:89], v17, s4, v[4:5]
	v_mov_b32_e32 v3, v4
	v_lshl_add_u64 v[2:3], v[2:3], 2, v[14:15]
	global_load_dwordx4 v[2:5], v[2:3], off nt

.LBB0_116:
	v_mov_b32_e32 v114, v115
	s_waitcnt vmcnt(0)
	ds_write2_b32 v38, v2, v3 offset1:1
	ds_write2_b32 v38, v4, v5 offset0:2 offset1:3
	v_mov_b32_e32 v116, v115
	v_mov_b32_e32 v117, v115
	v_add_u32_e32 v16, s80, v22
	v_mov_b64_e32 v[2:3], v[114:115]
	v_ashrrev_i32_e32 v17, 31, v16
	v_mov_b64_e32 v[4:5], v[116:117]
	s_and_saveexec_b64 vcc, s[38:39]
	s_cbranch_execz .LBB0_118
	v_mad_u64_u32 v[2:3], s[38:39], v16, s4, 0
	v_mov_b32_e32 v4, v3
	v_mad_u64_u32 v[4:5], s[38:39], v17, s4, v[4:5]
	v_mov_b32_e32 v3, v4
	v_lshl_add_u64 v[2:3], v[2:3], 2, v[14:15]
	global_load_dwordx4 v[2:5], v[2:3], off nt

.LBB0_146:
	global_load_dwordx4 v[14:17], v114, s[40:41] nt
	global_load_dwordx4 v[10:13], v114, s[40:41] offset:1024 nt
	v_lshl_add_u64 v[18:19], s[40:41], 0, v[114:115]
	s_waitcnt vmcnt(0)
	v_mul_f32_e32 v2, v15, v15
	v_mul_f32_e32 v3, v17, v17
	v_fmac_f32_e32 v2, v14, v14
	v_fmac_f32_e32 v3, v16, v16
	v_add_f32_e32 v2, v2, v3
	s_waitcnt vmcnt(0)
	v_mul_f32_e32 v3, v11, v11
	v_mul_f32_e32 v4, v13, v13
	v_fmac_f32_e32 v3, v10, v10
	v_fmac_f32_e32 v4, v12, v12
	v_add_f32_e32 v3, v3, v4
	v_add_f32_e32 v6, v2, v3
	global_load_dwordx4 v[2:5], v114, s[40:41] offset:2048 nt
	s_waitcnt vmcnt(0)
	v_mul_f32_e32 v7, v3, v3
	v_mul_f32_e32 v8, v5, v5
	v_fmac_f32_e32 v7, v2, v2
	v_fmac_f32_e32 v8, v4, v4
	v_add_f32_e32 v7, v7, v8
	v_add_f32_e32 v20, v6, v7
	global_load_dwordx4 v[6:9], v114, s[40:41] offset:3072 nt
	s_waitcnt vmcnt(0)
	v_mul_f32_e32 v21, v7, v7
	v_mul_f32_e32 v22, v9, v9
	v_fmac_f32_e32 v21, v6, v6
	v_fmac_f32_e32 v22, v8, v8
	v_add_f32_e32 v21, v21, v22
	v_add_co_u32_e32 v22, vcc, s63, v18
	v_add_f32_e32 v20, v20, v21
	s_nop 0
	v_addc_co_u32_e32 v23, vcc, 0, v19, vcc
	global_load_dwordx4 v[26:29], v[22:23], off nt
	global_load_dwordx4 v[30:33], v[22:23], off offset:1024 nt
	s_waitcnt vmcnt(1)
	v_mul_f32_e32 v18, v27, v27
	v_mul_f32_e32 v19, v29, v29
	v_fmac_f32_e32 v18, v26, v26
	v_fmac_f32_e32 v19, v28, v28
	v_add_f32_e32 v18, v18, v19
	v_add_f32_e32 v18, v20, v18
	s_waitcnt vmcnt(0)
	v_mul_f32_e32 v19, v31, v31
	v_mul_f32_e32 v20, v33, v33
	v_fmac_f32_e32 v19, v30, v30
	v_fmac_f32_e32 v20, v32, v32
	v_add_f32_e32 v19, v19, v20
	v_add_f32_e32 v24, v18, v19
	global_load_dwordx4 v[18:21], v[22:23], off offset:2048 nt
	s_waitcnt vmcnt(0)
	v_mul_f32_e32 v25, v19, v19
	v_mul_f32_e32 v49, v21, v21
	v_fmac_f32_e32 v25, v18, v18
	v_fmac_f32_e32 v49, v20, v20
	v_add_f32_e32 v25, v25, v49
	v_add_f32_e32 v49, v24, v25
	global_load_dwordx4 v[22:25], v[22:23], off offset:3072 nt
	s_waitcnt vmcnt(0)
	v_mul_f32_e32 v50, v23, v23
	v_mul_f32_e32 v51, v25, v25
	v_fmac_f32_e32 v50, v22, v22
	v_fmac_f32_e32 v51, v24, v24
	v_add_f32_e32 v50, v50, v51
	v_add_f32_e32 v49, v49, v50
	ds_bpermute_b32 v50, v37, v49
	s_waitcnt lgkmcnt(0)
	v_add_f32_e32 v49, v49, v50
	ds_bpermute_b32 v50, v44, v49
	s_waitcnt lgkmcnt(0)
	v_add_f32_e32 v49, v49, v50
	ds_bpermute_b32 v50, v45, v49
	s_waitcnt lgkmcnt(0)
	v_add_f32_e32 v49, v49, v50
	ds_bpermute_b32 v50, v46, v49
	s_waitcnt lgkmcnt(0)
	v_add_f32_e32 v49, v49, v50
	ds_bpermute_b32 v50, v47, v49
	s_waitcnt lgkmcnt(0)
	v_add_f32_e32 v49, v49, v50
	ds_bpermute_b32 v50, v48, v49
	s_waitcnt lgkmcnt(0)
	v_add_f32_e32 v49, v49, v50
	v_fmamk_f32 v49, v49, 0x3a000000, v1
	v_cmp_gt_f32_e32 vcc, s70, v49
	v_mul_f32_e32 v50, 0x4f800000, v49
	s_nop 0
	v_cndmask_b32_e32 v49, v49, v50, vcc
	v_sqrt_f32_e32 v50, v49
	s_nop 0
	v_add_u32_e32 v51, -1, v50
	v_fma_f32 v52, -v51, v50, v49
	v_cmp_ge_f32_e64 s[40:41], 0, v52
	v_add_u32_e32 v52, 1, v50
	s_nop 0
	v_cndmask_b32_e64 v51, v50, v51, s[40:41]
	v_fma_f32 v50, -v52, v50, v49
	v_cmp_lt_f32_e64 s[40:41], 0, v50
	s_nop 1
	v_cndmask_b32_e64 v50, v51, v52, s[40:41]
	v_mul_f32_e32 v51, 0x37800000, v50
	v_cndmask_b32_e32 v50, v50, v51, vcc
	v_cmp_class_f32_e32 vcc, v49, v226
	s_nop 1
	v_cndmask_b32_e32 v49, v50, v49, vcc
	v_div_scale_f32 v50, s[40:41], v49, v49, 1.0
	v_rcp_f32_e32 v51, v50
	s_nop 0
	v_fma_f32 v52, -v50, v51, 1.0
	v_fmac_f32_e32 v51, v52, v51
	v_div_scale_f32 v52, vcc, 1.0, v49, 1.0
	v_mul_f32_e32 v53, v52, v51
	v_fma_f32 v54, -v50, v53, v52
	v_fmac_f32_e32 v53, v54, v51
	v_fma_f32 v50, -v50, v53, v52
	v_div_fmas_f32 v50, v50, v51, v53
	v_div_fixup_f32 v49, v50, v49, 1.0
	s_and_saveexec_b64 s[40:41], s[38:39]
	s_cbranch_execz .LBB0_148
	s_lshl_b64 s[44:45], s[12:13], 2
	s_add_u32 s44, s1, s44
	s_addc_u32 s45, s3, s45
	global_store_dword v115, v49, s[44:45]

.LBB0_154:
	global_load_dwordx4 v[6:9], v[4:5], off offset:-16 nt
	global_load_dwordx4 v[10:13], v[4:5], off offset:-32 nt
	global_load_dwordx4 v[14:17], v[4:5], off offset:-64 nt
	global_load_dwordx4 v[18:21], v[4:5], off offset:-48 nt
	v_lshl_add_u64 v[38:39], v[38:39], 0, s[22:23]
	s_waitcnt vmcnt(0)
	v_pk_add_f32 v[16:17], v[16:17], v[20:21]
	v_pk_add_f32 v[14:15], v[14:15], v[18:19]
	v_pk_add_f32 v[12:13], v[16:17], v[12:13]
	v_pk_add_f32 v[10:11], v[14:15], v[10:11]
	v_pk_add_f32 v[22:23], v[12:13], v[8:9]
	v_pk_add_f32 v[24:25], v[10:11], v[6:7]
	global_load_dwordx4 v[6:9], v[4:5], off offset:48 nt
	global_load_dwordx4 v[10:13], v[4:5], off offset:32 nt
	global_load_dwordx4 v[14:17], v[4:5], off offset:16 nt
	global_load_dwordx4 v[18:21], v[4:5], off nt
	v_lshl_add_u64 v[4:5], v[4:5], 0, s[14:15]
	s_waitcnt vmcnt(0)
	v_pk_add_f32 v[20:21], v[22:23], v[20:21]
	v_pk_add_f32 v[18:19], v[24:25], v[18:19]
	v_pk_add_f32 v[16:17], v[20:21], v[16:17]
	v_pk_add_f32 v[14:15], v[18:19], v[14:15]
	v_pk_add_f32 v[12:13], v[16:17], v[12:13]
	v_pk_add_f32 v[10:11], v[14:15], v[10:11]
	v_pk_add_f32 v[8:9], v[12:13], v[8:9]
	v_pk_add_f32 v[6:7], v[10:11], v[6:7]
	s_nop 0
	v_pk_mov_b32 v[10:11], v[6:7], v[8:9] op_sel:[1,0]
	v_mov_b32_e32 v7, v9
	v_pk_add_f32 v[6:7], v[10:11], v[6:7]
	s_nop 0
	v_add_f32_e32 v6, v6, v7
	v_fmamk_f32 v6, v6, 0x3a000000, v1
	v_cmp_gt_f32_e32 vcc, s70, v6
	v_mul_f32_e32 v7, 0x4f800000, v6
	s_nop 0
	v_cndmask_b32_e32 v6, v6, v7, vcc
	v_sqrt_f32_e32 v7, v6
	s_nop 0
	v_add_u32_e32 v8, -1, v7
	v_fma_f32 v9, -v8, v7, v6
	v_cmp_ge_f32_e64 s[36:37], 0, v9
	v_add_u32_e32 v9, 1, v7
	s_nop 0
	v_cndmask_b32_e64 v8, v7, v8, s[36:37]
	v_fma_f32 v7, -v9, v7, v6
	v_cmp_lt_f32_e64 s[36:37], 0, v7
	s_nop 1
	v_cndmask_b32_e64 v7, v8, v9, s[36:37]
	v_mul_f32_e32 v8, 0x37800000, v7
	v_cndmask_b32_e32 v7, v7, v8, vcc
	v_cmp_class_f32_e32 vcc, v6, v226
	s_nop 1
	v_cndmask_b32_e32 v6, v7, v6, vcc
	v_div_scale_f32 v7, s[24:25], v6, v6, 1.0
	v_rcp_f32_e32 v8, v7
	s_nop 0
	v_fma_f32 v9, -v7, v8, 1.0
	v_fmac_f32_e32 v8, v9, v8
	v_div_scale_f32 v9, vcc, 1.0, v6, 1.0
	v_mul_f32_e32 v10, v9, v8
	v_fma_f32 v11, -v7, v10, v9
	v_fmac_f32_e32 v10, v11, v8
	v_fma_f32 v7, -v7, v10, v9
	v_div_fmas_f32 v7, v7, v8, v10
	v_div_fixup_f32 v6, v7, v6, 1.0
	v_cmp_lt_u64_e32 vcc, s[26:27], v[38:39]
	global_store_dword v[2:3], v6, off
	v_lshl_add_u64 v[2:3], v[2:3], 0, s[18:19]
	s_or_b64 s[16:17], vcc, s[16:17]
	s_andn2_b64 exec, exec, s[16:17]
	s_cbranch_execnz .LBB0_154

.LBB0_207:
	s_add_i32 s1, s0, 0x400
	s_cmpk_lt_i32 s0, 0x200
	s_cselect_b32 s18, s0, s1
	s_ashr_i32 s19, s18, 31
	s_lshl_b64 s[18:19], s[18:19], 12
	v_lshl_add_u64 v[6:7], v[2:3], 0, s[18:19]
	global_load_dwordx4 v[22:25], v[6:7], off nt
	global_load_dwordx4 v[30:33], v[6:7], off offset:1024 nt
	global_load_dwordx4 v[40:43], v[6:7], off offset:2048 nt
	global_load_dwordx4 v[44:47], v[6:7], off offset:3072 nt
	s_waitcnt vmcnt(0)
	v_lshlrev_b32_e32 v21, 16, v22
	v_and_b32_e32 v20, 0xffff0000, v22
	v_max_f32_e64 v14, |v20|, |v20|
	v_max_f32_e64 v15, |v21|, |v21|
	v_lshlrev_b32_e32 v19, 16, v23
	v_and_b32_e32 v18, 0xffff0000, v23
	v_max_f32_e32 v14, v15, v14
	v_max_f32_e64 v15, |v18|, |v18|
	v_max_f32_e64 v16, |v19|, |v19|
	v_max_f32_e32 v15, v16, v15
	v_lshlrev_b32_e32 v17, 16, v24
	v_and_b32_e32 v16, 0xffff0000, v24
	v_max3_f32 v22, v14, 0, v15
	v_max_f32_e64 v14, |v16|, |v16|
	v_max_f32_e64 v15, |v17|, |v17|
	v_max_f32_e32 v23, v15, v14
	v_lshlrev_b32_e32 v15, 16, v25
	v_and_b32_e32 v14, 0xffff0000, v25
	v_max_f32_e64 v24, |v14|, |v14|
	v_max_f32_e64 v25, |v15|, |v15|
	v_max_f32_e32 v24, v25, v24
	s_waitcnt vmcnt(2)
	v_lshlrev_b32_e32 v29, 16, v30
	v_and_b32_e32 v28, 0xffff0000, v30
	v_max3_f32 v22, v22, v23, v24
	v_max_f32_e64 v23, |v28|, |v28|
	v_max_f32_e64 v24, |v29|, |v29|
	v_lshlrev_b32_e32 v27, 16, v31
	v_and_b32_e32 v26, 0xffff0000, v31
	v_max_f32_e32 v23, v24, v23
	v_max_f32_e64 v24, |v26|, |v26|
	v_max_f32_e64 v25, |v27|, |v27|
	v_max_f32_e32 v24, v25, v24
	v_max3_f32 v30, v22, v23, v24
	v_lshlrev_b32_e32 v25, 16, v32
	v_and_b32_e32 v24, 0xffff0000, v32
	v_max_f32_e64 v22, |v24|, |v24|
	v_max_f32_e64 v23, |v25|, |v25|
	v_max_f32_e32 v31, v23, v22
	v_lshlrev_b32_e32 v23, 16, v33
	v_and_b32_e32 v22, 0xffff0000, v33
	v_max_f32_e64 v32, |v22|, |v22|
	v_max_f32_e64 v33, |v23|, |v23|
	v_max_f32_e32 v32, v33, v32
	s_waitcnt vmcnt(1)
	v_lshlrev_b32_e32 v39, 16, v40
	v_and_b32_e32 v38, 0xffff0000, v40
	v_max3_f32 v30, v30, v31, v32
	v_max_f32_e64 v31, |v38|, |v38|
	v_max_f32_e64 v32, |v39|, |v39|
	v_lshlrev_b32_e32 v37, 16, v41
	v_and_b32_e32 v35, 0xffff0000, v41
	v_max_f32_e32 v31, v32, v31
	v_max_f32_e64 v32, |v35|, |v35|
	v_max_f32_e64 v33, |v37|, |v37|
	v_max_f32_e32 v32, v33, v32
	v_max3_f32 v40, v30, v31, v32
	v_lshlrev_b32_e32 v33, 16, v42
	v_and_b32_e32 v32, 0xffff0000, v42
	v_max_f32_e64 v30, |v32|, |v32|
	v_max_f32_e64 v31, |v33|, |v33|
	v_max_f32_e32 v41, v31, v30
	v_lshlrev_b32_e32 v31, 16, v43
	v_and_b32_e32 v30, 0xffff0000, v43
	v_max_f32_e64 v42, |v30|, |v30|
	v_max_f32_e64 v43, |v31|, |v31|
	v_max_f32_e32 v42, v43, v42
	s_waitcnt vmcnt(0)
	v_lshlrev_b32_e32 v7, 16, v44
	v_and_b32_e32 v6, 0xffff0000, v44
	v_max3_f32 v42, v40, v41, v42
	v_max_f32_e64 v40, |v6|, |v6|
	v_max_f32_e64 v41, |v7|, |v7|
	v_max_f32_e32 v43, v41, v40
	v_lshlrev_b32_e32 v41, 16, v45
	v_and_b32_e32 v40, 0xffff0000, v45
	v_max_f32_e64 v44, |v40|, |v40|
	v_max_f32_e64 v45, |v41|, |v41|
	v_max_f32_e32 v44, v45, v44
	v_max3_f32 v48, v42, v43, v44
	v_lshlrev_b32_e32 v44, 16, v46
	v_and_b32_e32 v42, 0xffff0000, v46
	v_max_f32_e64 v43, |v42|, |v42|
	v_max_f32_e64 v45, |v44|, |v44|
	v_max_f32_e32 v46, v45, v43
	v_lshlrev_b32_e32 v45, 16, v47
	v_and_b32_e32 v43, 0xffff0000, v47
	v_max_f32_e64 v47, |v43|, |v43|
	v_max_f32_e64 v49, |v45|, |v45|
	v_max_f32_e32 v47, v49, v47
	v_max3_f32 v46, v48, v46, v47
	ds_bpermute_b32 v47, v8, v46
	s_waitcnt lgkmcnt(0)
	v_max_f32_e32 v47, v47, v47
	v_max_f32_e32 v46, v46, v47
	ds_bpermute_b32 v47, v9, v46
	s_waitcnt lgkmcnt(0)
	v_max_f32_e32 v47, v47, v47
	v_max_f32_e32 v46, v46, v47
	ds_bpermute_b32 v47, v10, v46
	s_waitcnt lgkmcnt(0)
	v_max_f32_e32 v47, v47, v47
	v_max_f32_e32 v46, v46, v47
	ds_bpermute_b32 v47, v11, v46
	s_waitcnt lgkmcnt(0)
	v_max_f32_e32 v47, v47, v47
	v_max_f32_e32 v46, v46, v47
	ds_bpermute_b32 v47, v12, v46
	s_waitcnt lgkmcnt(0)
	v_max_f32_e32 v47, v47, v47
	v_max_f32_e32 v46, v46, v47
	ds_bpermute_b32 v47, v13, v46
	s_waitcnt lgkmcnt(0)
	v_max3_f32 v46, v46, v47, s73
	s_and_saveexec_b64 s[18:19], s[36:37]
	s_cbranch_execz .LBB0_206
	v_mul_f32_e32 v47, 0x3c010204, v46
	global_store_dword v115, v47, s[12:13]
	s_branch .LBB0_206

.LBB0_212:
	global_load_dwordx4 v[20:23], v[2:3], off offset:-2048 nt
	global_load_dwordx4 v[28:31], v[2:3], off offset:-1024 nt
	global_load_dwordx4 v[36:39], v[2:3], off nt
	global_load_dwordx4 v[42:45], v[2:3], off offset:1024 nt
	s_waitcnt vmcnt(0)
	v_lshlrev_b32_e32 v19, 16, v20
	v_and_b32_e32 v18, 0xffff0000, v20
	v_max_f32_e64 v12, |v18|, |v18|
	v_max_f32_e64 v13, |v19|, |v19|
	v_lshlrev_b32_e32 v17, 16, v21
	v_and_b32_e32 v16, 0xffff0000, v21
	v_max_f32_e32 v12, v13, v12
	v_max_f32_e64 v13, |v16|, |v16|
	v_max_f32_e64 v14, |v17|, |v17|
	v_max_f32_e32 v13, v14, v13
	v_lshlrev_b32_e32 v15, 16, v22
	v_and_b32_e32 v14, 0xffff0000, v22
	v_max3_f32 v20, v12, 0, v13
	v_max_f32_e64 v12, |v14|, |v14|
	v_max_f32_e64 v13, |v15|, |v15|
	v_max_f32_e32 v21, v13, v12
	v_lshlrev_b32_e32 v13, 16, v23
	v_and_b32_e32 v12, 0xffff0000, v23
	v_max_f32_e64 v22, |v12|, |v12|
	v_max_f32_e64 v23, |v13|, |v13|
	v_max_f32_e32 v22, v23, v22
	s_waitcnt vmcnt(2)
	v_lshlrev_b32_e32 v27, 16, v28
	v_and_b32_e32 v26, 0xffff0000, v28
	v_max3_f32 v20, v20, v21, v22
	v_max_f32_e64 v21, |v26|, |v26|
	v_max_f32_e64 v22, |v27|, |v27|
	v_lshlrev_b32_e32 v25, 16, v29
	v_and_b32_e32 v24, 0xffff0000, v29
	v_max_f32_e32 v21, v22, v21
	v_max_f32_e64 v22, |v24|, |v24|
	v_max_f32_e64 v23, |v25|, |v25|
	v_max_f32_e32 v22, v23, v22
	v_max3_f32 v28, v20, v21, v22
	v_lshlrev_b32_e32 v23, 16, v30
	v_and_b32_e32 v22, 0xffff0000, v30
	v_max_f32_e64 v20, |v22|, |v22|
	v_max_f32_e64 v21, |v23|, |v23|
	v_max_f32_e32 v29, v21, v20
	v_lshlrev_b32_e32 v21, 16, v31
	v_and_b32_e32 v20, 0xffff0000, v31
	v_max_f32_e64 v30, |v20|, |v20|
	v_max_f32_e64 v31, |v21|, |v21|
	v_max_f32_e32 v30, v31, v30
	s_waitcnt vmcnt(1)
	v_lshlrev_b32_e32 v35, 16, v36
	v_and_b32_e32 v34, 0xffff0000, v36
	v_max3_f32 v28, v28, v29, v30
	v_max_f32_e64 v29, |v34|, |v34|
	v_max_f32_e64 v30, |v35|, |v35|
	v_lshlrev_b32_e32 v33, 16, v37
	v_and_b32_e32 v32, 0xffff0000, v37
	v_max_f32_e32 v29, v30, v29
	v_max_f32_e64 v30, |v32|, |v32|
	v_max_f32_e64 v31, |v33|, |v33|
	v_max_f32_e32 v30, v31, v30
	v_max3_f32 v36, v28, v29, v30
	v_lshlrev_b32_e32 v31, 16, v38
	v_and_b32_e32 v30, 0xffff0000, v38
	v_max_f32_e64 v28, |v30|, |v30|
	v_max_f32_e64 v29, |v31|, |v31|
	v_max_f32_e32 v37, v29, v28
	v_lshlrev_b32_e32 v29, 16, v39
	v_and_b32_e32 v28, 0xffff0000, v39
	v_max_f32_e64 v38, |v28|, |v28|
	v_max_f32_e64 v39, |v29|, |v29|
	v_max_f32_e32 v38, v39, v38
	v_max3_f32 v40, v36, v37, v38
	s_waitcnt vmcnt(0)
	v_lshlrev_b32_e32 v37, 16, v42
	v_and_b32_e32 v36, 0xffff0000, v42
	v_max_f32_e64 v38, |v36|, |v36|
	v_max_f32_e64 v39, |v37|, |v37|
	v_max_f32_e32 v41, v39, v38
	v_lshlrev_b32_e32 v39, 16, v43
	v_and_b32_e32 v38, 0xffff0000, v43
	v_max_f32_e64 v42, |v38|, |v38|
	v_max_f32_e64 v43, |v39|, |v39|
	v_max_f32_e32 v42, v43, v42
	v_max3_f32 v46, v40, v41, v42
	v_lshlrev_b32_e32 v42, 16, v44
	v_and_b32_e32 v40, 0xffff0000, v44
	v_max_f32_e64 v41, |v40|, |v40|
	v_max_f32_e64 v43, |v42|, |v42|
	v_max_f32_e32 v44, v43, v41
	v_lshlrev_b32_e32 v43, 16, v45
	v_and_b32_e32 v41, 0xffff0000, v45
	v_max_f32_e64 v45, |v41|, |v41|
	v_max_f32_e64 v47, |v43|, |v43|
	v_max_f32_e32 v45, v47, v45
	v_max3_f32 v44, v46, v44, v45
	ds_bpermute_b32 v45, v6, v44
	s_waitcnt lgkmcnt(0)
	v_max_f32_e32 v45, v45, v45
	v_max_f32_e32 v44, v44, v45
	ds_bpermute_b32 v45, v7, v44
	s_waitcnt lgkmcnt(0)
	v_max_f32_e32 v45, v45, v45
	v_max_f32_e32 v44, v44, v45
	ds_bpermute_b32 v45, v8, v44
	s_waitcnt lgkmcnt(0)
	v_max_f32_e32 v45, v45, v45
	v_max_f32_e32 v44, v44, v45
	ds_bpermute_b32 v45, v9, v44
	s_waitcnt lgkmcnt(0)
	v_max_f32_e32 v45, v45, v45
	v_max_f32_e32 v44, v44, v45
	ds_bpermute_b32 v45, v10, v44
	s_waitcnt lgkmcnt(0)
	v_max_f32_e32 v45, v45, v45
	v_max_f32_e32 v44, v44, v45
	ds_bpermute_b32 v45, v11, v44
	s_waitcnt lgkmcnt(0)
	v_max3_f32 v44, v44, v45, s73
	s_and_saveexec_b64 s[10:11], s[36:37]
	s_cbranch_execz .LBB0_211
	global_load_dword v45, v115, s[0:1]
	v_mul_f32_e32 v46, 0x3c010204, v44
	s_waitcnt vmcnt(0)
	v_mul_f32_e32 v45, v45, v46
	v_mov_b32_e32 v46, 0x65b2000
	global_store_dword v46, v45, s[0:1]
	s_branch .LBB0_211

.LBB0_874:
	global_load_dwordx4 v[10:13], v[2:3], off nt
	global_load_dwordx4 v[14:17], v[2:3], off offset:16 nt
	s_add_i32 s3, s3, -1
	s_cmp_eq_u32 s3, 0
	s_waitcnt vmcnt(0)
	v_lshlrev_b32_e32 v27, 16, v11
	v_lshlrev_b32_e32 v26, 16, v10
	v_and_b32_e32 v11, 0xffff0000, v11
	v_and_b32_e32 v10, 0xffff0000, v10
	v_pk_mul_f32 v[28:29], v[10:11], v[10:11]
	v_lshlrev_b32_e32 v31, 16, v13
	v_lshlrev_b32_e32 v30, 16, v12
	v_and_b32_e32 v13, 0xffff0000, v13
	v_and_b32_e32 v12, 0xffff0000, v12
	v_pk_fma_f32 v[28:29], v[26:27], v[26:27], v[28:29]
	v_pk_mul_f32 v[32:33], v[12:13], v[12:13]
	v_lshlrev_b32_e32 v19, 16, v15
	v_lshlrev_b32_e32 v18, 16, v14
	v_and_b32_e32 v15, 0xffff0000, v15
	v_and_b32_e32 v14, 0xffff0000, v14
	v_pk_fma_f32 v[32:33], v[30:31], v[30:31], v[32:33]
	v_add_f32_e32 v28, v28, v29
	v_pk_mul_f32 v[20:21], v[14:15], v[14:15]
	v_add_f32_e32 v28, v32, v28
	v_pk_fma_f32 v[20:21], v[18:19], v[18:19], v[20:21]
	v_lshlrev_b32_e32 v23, 16, v17
	v_lshlrev_b32_e32 v22, 16, v16
	v_and_b32_e32 v17, 0xffff0000, v17
	v_and_b32_e32 v16, 0xffff0000, v16
	v_add_f32_e32 v28, v33, v28
	v_pk_mul_f32 v[24:25], v[16:17], v[16:17]
	v_add_f32_e32 v20, v20, v28
	v_pk_fma_f32 v[24:25], v[22:23], v[22:23], v[24:25]
	v_add_f32_e32 v20, v21, v20
	v_add_f32_e32 v20, v24, v20
	v_add_f32_e32 v20, v25, v20
	ds_bpermute_b32 v21, v4, v20
	s_waitcnt lgkmcnt(0)
	v_add_f32_e32 v20, v20, v21
	ds_bpermute_b32 v21, v5, v20
	s_waitcnt lgkmcnt(0)
	v_add_f32_e32 v20, v20, v21
	ds_bpermute_b32 v21, v6, v20
	s_waitcnt lgkmcnt(0)
	v_add_f32_e32 v20, v20, v21
	ds_bpermute_b32 v21, v7, v20
	s_waitcnt lgkmcnt(0)
	v_add_f32_e32 v20, v20, v21
	ds_bpermute_b32 v21, v8, v20
	s_waitcnt lgkmcnt(0)
	v_add_f32_e32 v20, v20, v21
	ds_bpermute_b32 v21, v9, v20
	s_waitcnt lgkmcnt(0)
	v_add_f32_e32 v20, v20, v21
	v_fmamk_f32 v20, v20, 0x3a800000, v1
	v_cmp_gt_f32_e32 vcc, s70, v20
	v_mul_f32_e32 v21, 0x4f800000, v20
	s_nop 0
	v_cndmask_b32_e32 v20, v20, v21, vcc
	v_sqrt_f32_e32 v21, v20
	s_nop 0
	v_add_u32_e32 v24, -1, v21
	v_fma_f32 v25, -v24, v21, v20
	v_cmp_ge_f32_e64 s[36:37], 0, v25
	v_add_u32_e32 v25, 1, v21
	s_nop 0
	v_cndmask_b32_e64 v24, v21, v24, s[36:37]
	v_fma_f32 v21, -v25, v21, v20
	v_cmp_lt_f32_e64 s[36:37], 0, v21
	s_nop 1
	v_cndmask_b32_e64 v21, v24, v25, s[36:37]
	v_mul_f32_e32 v24, 0x37800000, v21
	v_cndmask_b32_e32 v21, v21, v24, vcc
	v_cmp_class_f32_e32 vcc, v20, v226
	s_nop 1
	v_cndmask_b32_e32 v20, v21, v20, vcc
	v_div_scale_f32 v21, s[6:7], v20, v20, 1.0
	v_rcp_f32_e32 v24, v21
	s_nop 0
	v_fma_f32 v25, -v21, v24, 1.0
	v_fmac_f32_e32 v24, v25, v24
	v_div_scale_f32 v25, vcc, 1.0, v20, 1.0
	v_mul_f32_e32 v28, v25, v24
	v_fma_f32 v29, -v21, v28, v25
	v_fmac_f32_e32 v28, v29, v24
	v_fma_f32 v21, -v21, v28, v25
	v_div_fmas_f32 v21, v21, v24, v28
	v_div_fixup_f32 v20, v21, v20, 1.0
	v_pk_mul_f32 v[12:13], v[20:21], v[12:13] op_sel_hi:[0,1]
	v_pk_mul_f32 v[24:25], v[20:21], v[26:27] op_sel_hi:[0,1]
	v_pk_mul_f32 v[10:11], v[20:21], v[10:11] op_sel_hi:[0,1]
	v_pk_mul_f32 v[26:27], v[20:21], v[30:31] op_sel_hi:[0,1]
	v_bfe_u32 v21, v13, 16, 1
	v_bfe_u32 v28, v12, 16, 1
	v_bfe_u32 v29, v11, 16, 1
	v_add3_u32 v13, v13, v21, s67
	v_bfe_u32 v21, v24, 16, 1
	v_add3_u32 v11, v11, v29, s67
	v_add3_u32 v12, v12, v28, s67
	v_bfe_u32 v28, v25, 16, 1
	v_bfe_u32 v29, v26, 16, 1
	v_add3_u32 v21, v24, v21, s67
	v_bfe_u32 v30, v10, 16, 1
	v_add3_u32 v26, v26, v29, s67
	v_add3_u32 v25, v25, v28, s67
	v_lshrrev_b32_e32 v21, 16, v21
	v_add3_u32 v10, v10, v30, s67
	v_lshrrev_b32_e32 v24, 16, v25
	v_lshrrev_b32_e32 v25, 16, v26
	v_pk_mul_f32 v[14:15], v[20:21], v[14:15] op_sel_hi:[0,1]
	v_pk_mul_f32 v[16:17], v[20:21], v[16:17] op_sel_hi:[0,1]
	v_bfe_u32 v30, v27, 16, 1
	v_and_or_b32 v12, v12, s8, v25
	v_and_or_b32 v11, v11, s8, v24
	v_and_or_b32 v10, v10, s8, v21
	v_pk_mul_f32 v[18:19], v[20:21], v[18:19] op_sel_hi:[0,1]
	v_pk_mul_f32 v[22:23], v[20:21], v[22:23] op_sel_hi:[0,1]
	v_bfe_u32 v20, v17, 16, 1
	v_bfe_u32 v21, v16, 16, 1
	v_bfe_u32 v24, v15, 16, 1
	v_bfe_u32 v25, v14, 16, 1
	v_add3_u32 v27, v27, v30, s67
	v_add3_u32 v14, v14, v25, s67
	v_add3_u32 v15, v15, v24, s67
	v_add3_u32 v16, v16, v21, s67
	v_add3_u32 v17, v17, v20, s67
	v_bfe_u32 v20, v18, 16, 1
	v_bfe_u32 v21, v19, 16, 1
	v_bfe_u32 v24, v22, 16, 1
	v_bfe_u32 v25, v23, 16, 1
	v_lshrrev_b32_e32 v26, 16, v27
	v_add3_u32 v23, v23, v25, s67
	v_add3_u32 v22, v22, v24, s67
	v_add3_u32 v19, v19, v21, s67
	v_add3_u32 v18, v18, v20, s67
	v_and_or_b32 v13, v13, s8, v26
	v_lshrrev_b32_e32 v18, 16, v18
	v_lshrrev_b32_e32 v19, 16, v19
	v_lshrrev_b32_e32 v20, 16, v22
	v_lshrrev_b32_e32 v21, 16, v23
	v_and_or_b32 v17, v17, s8, v21
	v_and_or_b32 v16, v16, s8, v20
	v_and_or_b32 v15, v15, s8, v19
	v_and_or_b32 v14, v14, s8, v18
	global_store_dwordx4 v[2:3], v[10:13], off nt
	global_store_dwordx4 v[2:3], v[14:17], off offset:16 nt
	v_lshl_add_u64 v[2:3], v[2:3], 0, s[0:1]
	s_cbranch_scc0 .LBB0_874

.LBB0_943:
	s_lshl_b32 s20, s20, 8
	s_ashr_i32 s21, s20, 31
	s_lshl_b32 s3, s18, 8
	s_lshl_b64 s[22:23], s[20:21], 11
	s_ashr_i32 s4, s3, 31
	s_add_u32 s22, s22, s3
	s_addc_u32 s23, s23, s4
	s_lshl_b64 s[22:23], s[22:23], 1
	v_lshl_add_u64 v[158:159], v[150:151], 0, s[22:23]
	global_load_dwordx4 v[168:171], v[158:159], off nt
	global_load_dwordx4 v[172:175], v[158:159], off offset:64 nt
	s_mov_b32 s3, 0x10000
	v_add_co_u32_e32 v132, vcc, s3, v158
	v_mov_b32_e32 v157, v115
	s_nop 0
	v_addc_co_u32_e32 v133, vcc, 0, v159, vcc
	global_load_dwordx4 v[136:139], v[132:133], off nt
	s_nop 0
	global_load_dwordx4 v[132:135], v[132:133], off offset:64 nt
	v_mov_b32_e32 v160, v115
	v_mov_b32_e32 v161, v115
	v_add_u32_e32 v156, s20, v164
	s_add_u32 s20, s51, s22
	s_addc_u32 s21, s52, s23
	s_lshl_b32 s18, s18, 2
	s_ashr_i32 s19, s18, 31
	s_waitcnt vmcnt(0)
	v_lshlrev_b32_e32 v167, 16, v168
	v_and_b32_e32 v168, 0xffff0000, v168
	v_lshlrev_b32_e32 v176, 16, v169
	v_and_b32_e32 v169, 0xffff0000, v169
	v_lshlrev_b32_e32 v177, 16, v170
	v_and_b32_e32 v170, 0xffff0000, v170
	v_lshlrev_b32_e32 v178, 16, v171
	v_and_b32_e32 v171, 0xffff0000, v171
	v_lshlrev_b32_e32 v181, 16, v174
	v_and_b32_e32 v174, 0xffff0000, v174
	v_lshlrev_b32_e32 v182, 16, v175
	v_and_b32_e32 v175, 0xffff0000, v175
	v_add_f32_e32 v129, v129, v168
	v_add_f32_e32 v131, v131, v169
	v_add_f32_e32 v125, v125, v170
	v_add_f32_e32 v127, v127, v171
	v_lshlrev_b32_e32 v179, 16, v172
	v_and_b32_e32 v172, 0xffff0000, v172
	v_lshlrev_b32_e32 v180, 16, v173
	v_and_b32_e32 v173, 0xffff0000, v173
	v_add_f32_e32 v128, v128, v167
	v_add_f32_e32 v130, v130, v176
	v_add_f32_e32 v124, v124, v177
	v_add_f32_e32 v126, v126, v178
	v_add_f32_e32 v117, v117, v174
	v_add_f32_e32 v119, v119, v175
	v_cvt_pk_bf16_f32 v167, v128, v129
	v_cvt_pk_bf16_f32 v168, v130, v131
	v_cvt_pk_bf16_f32 v169, v124, v125
	v_cvt_pk_bf16_f32 v170, v126, v127
	v_mul_f32_e32 v129, v129, v129
	v_mul_f32_e32 v131, v131, v131
	v_mul_f32_e32 v125, v125, v125
	v_mul_f32_e32 v127, v127, v127
	v_add_f32_e32 v120, v120, v179
	v_add_f32_e32 v121, v121, v172
	v_add_f32_e32 v122, v122, v180
	v_add_f32_e32 v123, v123, v173
	v_add_f32_e32 v116, v116, v181
	v_add_f32_e32 v118, v118, v182
	v_cvt_pk_bf16_f32 v171, v120, v121
	v_cvt_pk_bf16_f32 v172, v122, v123
	v_cvt_pk_bf16_f32 v173, v116, v117
	v_cvt_pk_bf16_f32 v174, v118, v119
	v_mul_f32_e32 v117, v117, v117
	v_mul_f32_e32 v119, v119, v119
	v_fmac_f32_e32 v129, v128, v128
	v_fmac_f32_e32 v131, v130, v130
	v_fmac_f32_e32 v125, v124, v124
	v_fmac_f32_e32 v127, v126, v126
	v_fmac_f32_e32 v117, v116, v116
	v_fmac_f32_e32 v119, v118, v118
	v_add_f32_e32 v124, v129, v131
	v_add_f32_e32 v125, v125, v127
	v_mul_f32_e32 v121, v121, v121
	v_mul_f32_e32 v123, v123, v123
	v_cndmask_b32_e64 v116, v174, v170, s[36:37]
	v_add_f32_e32 v117, v117, v119
	v_add_f32_e32 v119, v124, v125
	v_mov_b32_e32 v124, v115
	v_and_b32_e32 v125, 64, v234
	v_fmac_f32_e32 v121, v120, v120
	v_fmac_f32_e32 v123, v122, v122
	v_mov_b32_dpp v124, v116 quad_perm:[1,0,3,2] row_mask:0xf bank_mask:0xf
	v_xor_b32_e32 v116, 16, v234
	v_add_u32_e32 v125, 64, v125
	v_add_f32_e32 v121, v121, v123
	v_cmp_lt_i32_e32 vcc, v116, v125
	v_add_f32_e32 v117, v121, v117
	v_add_f32_e32 v117, v119, v117
	v_cndmask_b32_e32 v116, v234, v116, vcc
	v_lshlrev_b32_e32 v116, 2, v116
	ds_bpermute_b32 v126, v116, v117
	v_cndmask_b32_e64 v118, v173, v169, s[36:37]
	v_cndmask_b32_e64 v120, v172, v168, s[36:37]
	v_cndmask_b32_e64 v122, v171, v167, s[36:37]
	v_mov_b32_dpp v161, v118 quad_perm:[1,0,3,2] row_mask:0xf bank_mask:0xf
	v_mov_b32_dpp v160, v120 quad_perm:[1,0,3,2] row_mask:0xf bank_mask:0xf
	v_mov_b32_dpp v157, v122 quad_perm:[1,0,3,2] row_mask:0xf bank_mask:0xf
	v_cndmask_b32_e64 v118, v167, v157, s[36:37]
	v_cndmask_b32_e64 v119, v168, v160, s[36:37]
	v_cndmask_b32_e64 v120, v169, v161, s[36:37]
	v_cndmask_b32_e64 v121, v170, v124, s[36:37]
	v_lshl_add_u64 v[122:123], v[146:147], 1, s[20:21]
	global_store_dwordx4 v[122:123], v[118:121], off nt
	v_cndmask_b32_e64 v122, v161, v173, s[36:37]
	v_cndmask_b32_e64 v123, v124, v174, s[36:37]
	s_waitcnt lgkmcnt(0)
	v_add_f32_e32 v118, v117, v126
	v_xor_b32_e32 v117, 32, v234
	v_cmp_lt_i32_e32 vcc, v117, v125
	v_cndmask_b32_e64 v120, v157, v171, s[36:37]
	v_cndmask_b32_e64 v121, v160, v172, s[36:37]
	v_cndmask_b32_e32 v117, v234, v117, vcc
	v_lshlrev_b32_e32 v117, 2, v117
	ds_bpermute_b32 v119, v117, v118
	v_lshl_add_u64 v[124:125], v[148:149], 1, s[20:21]
	v_ashrrev_i32_e32 v157, 31, v156
	global_store_dwordx4 v[124:125], v[120:123], off nt
	s_and_saveexec_b64 s[22:23], s[38:39]
	s_cbranch_execz .LBB0_945
	v_lshlrev_b64 v[120:121], 7, v[156:157]
	v_lshl_add_u64 v[120:121], s[6:7], 0, v[120:121]
	v_lshl_add_u64 v[120:121], s[18:19], 2, v[120:121]
	s_lshl_b32 s4, s53, 2
	v_lshl_add_u64 v[120:121], v[120:121], 0, s[4:5]
	s_waitcnt lgkmcnt(0)
	v_add_f32_e32 v118, v118, v119
	global_store_dword v[120:121], v118, off nt

.LBB0_947:
	s_or_b64 exec, exec, s[22:23]
	v_add_co_u32_e32 v82, vcc, 0x20000, v158
	s_add_u32 s22, s20, 0x20000
	s_waitcnt lgkmcnt(0)
	v_addc_co_u32_e32 v83, vcc, 0, v159, vcc
	global_load_dwordx4 v[106:109], v[82:83], off nt
	global_load_dwordx4 v[110:113], v[82:83], off offset:64 nt
	v_add_co_u32_e32 v82, vcc, 0x30000, v158
	s_addc_u32 s23, s21, 0
	s_nop 0
	v_addc_co_u32_e32 v83, vcc, 0, v159, vcc
	global_load_dwordx4 v[86:89], v[82:83], off nt
	s_nop 0
	global_load_dwordx4 v[82:85], v[82:83], off offset:64 nt
	s_waitcnt vmcnt(3)
	v_lshlrev_b32_e32 v118, 16, v106
	v_and_b32_e32 v106, 0xffff0000, v106
	v_add_f32_e32 v103, v103, v106
	v_lshlrev_b32_e32 v106, 16, v107
	v_add_f32_e32 v104, v104, v106
	v_and_b32_e32 v106, 0xffff0000, v107
	v_add_f32_e32 v105, v105, v106
	v_lshlrev_b32_e32 v106, 16, v108
	v_add_f32_e32 v106, v98, v106
	v_and_b32_e32 v98, 0xffff0000, v108
	v_add_f32_e32 v107, v99, v98
	v_lshlrev_b32_e32 v98, 16, v109
	v_add_f32_e32 v108, v100, v98
	v_and_b32_e32 v98, 0xffff0000, v109
	v_add_f32_e32 v102, v102, v118
	v_add_f32_e32 v109, v101, v98
	v_cvt_pk_bf16_f32 v98, v102, v103
	v_mul_f32_e32 v103, v103, v103
	v_fmac_f32_e32 v103, v102, v102
	v_mul_f32_e32 v102, v105, v105
	v_fmac_f32_e32 v102, v104, v104
	v_cvt_pk_bf16_f32 v99, v104, v105
	v_add_f32_e32 v102, v103, v102
	v_mul_f32_e32 v103, v107, v107
	v_mul_f32_e32 v104, v109, v109
	v_fmac_f32_e32 v103, v106, v106
	v_fmac_f32_e32 v104, v108, v108
	v_add_f32_e32 v103, v103, v104
	v_add_f32_e32 v102, v102, v103
	s_waitcnt vmcnt(2)
	v_lshlrev_b32_e32 v103, 16, v110
	v_add_f32_e32 v103, v94, v103
	v_and_b32_e32 v94, 0xffff0000, v110
	v_add_f32_e32 v95, v95, v94
	v_lshlrev_b32_e32 v94, 16, v111
	v_add_f32_e32 v96, v96, v94
	v_and_b32_e32 v94, 0xffff0000, v111
	v_add_f32_e32 v97, v97, v94
	v_lshlrev_b32_e32 v94, 16, v112
	v_add_f32_e32 v90, v90, v94
	v_and_b32_e32 v94, 0xffff0000, v112
	v_add_f32_e32 v104, v91, v94
	v_lshlrev_b32_e32 v91, 16, v113
	v_add_f32_e32 v105, v92, v91
	v_and_b32_e32 v91, 0xffff0000, v113
	v_cvt_pk_bf16_f32 v100, v106, v107
	v_cvt_pk_bf16_f32 v101, v108, v109
	v_add_f32_e32 v106, v93, v91
	v_cvt_pk_bf16_f32 v91, v103, v95
	v_cvt_pk_bf16_f32 v92, v96, v97
	v_mul_f32_e32 v97, v97, v97
	v_fmac_f32_e32 v97, v96, v96
	v_mul_f32_e32 v96, v104, v104
	v_cvt_pk_bf16_f32 v93, v90, v104
	v_mul_f32_e32 v95, v95, v95
	v_fmac_f32_e32 v96, v90, v90
	v_mul_f32_e32 v90, v106, v106
	v_fmac_f32_e32 v95, v103, v103
	v_fmac_f32_e32 v90, v105, v105
	v_add_f32_e32 v95, v95, v97
	v_add_f32_e32 v90, v96, v90
	v_add_f32_e32 v90, v95, v90
	v_add_f32_e32 v90, v102, v90
	v_cndmask_b32_e64 v102, v91, v98, s[36:37]
	v_mov_b32_e32 v103, v115
	v_cvt_pk_bf16_f32 v94, v105, v106
	v_cndmask_b32_e64 v96, v93, v100, s[36:37]
	v_cndmask_b32_e64 v95, v94, v101, s[36:37]
	v_cndmask_b32_e64 v97, v92, v99, s[36:37]
	v_mov_b32_dpp v103, v102 quad_perm:[1,0,3,2] row_mask:0xf bank_mask:0xf
	v_mov_b32_e32 v102, v115
	v_mov_b32_e32 v104, v115
	v_mov_b32_e32 v105, v115
	v_mov_b32_dpp v102, v97 quad_perm:[1,0,3,2] row_mask:0xf bank_mask:0xf
	v_mov_b32_dpp v104, v96 quad_perm:[1,0,3,2] row_mask:0xf bank_mask:0xf
	v_mov_b32_dpp v105, v95 quad_perm:[1,0,3,2] row_mask:0xf bank_mask:0xf
	v_cndmask_b32_e64 v96, v98, v103, s[36:37]
	v_cndmask_b32_e64 v97, v99, v102, s[36:37]
	v_cndmask_b32_e64 v98, v100, v104, s[36:37]
	v_cndmask_b32_e64 v99, v101, v105, s[36:37]
	v_lshl_add_u64 v[100:101], v[146:147], 1, s[22:23]
	global_store_dwordx4 v[100:101], v[96:99], off nt
	s_nop 1
	v_cndmask_b32_e64 v96, v103, v91, s[36:37]
	ds_bpermute_b32 v91, v116, v90
	v_cndmask_b32_e64 v97, v102, v92, s[36:37]
	v_cndmask_b32_e64 v98, v104, v93, s[36:37]
	v_cndmask_b32_e64 v99, v105, v94, s[36:37]
	v_lshl_add_u64 v[92:93], v[148:149], 1, s[22:23]
	s_waitcnt lgkmcnt(0)
	v_add_f32_e32 v90, v90, v91
	ds_bpermute_b32 v91, v117, v90
	global_store_dwordx4 v[92:93], v[96:99], off nt
	s_and_saveexec_b64 s[22:23], s[38:39]
	s_cbranch_execz .LBB0_949
	s_waitcnt lgkmcnt(0)
	v_add_f32_e32 v92, v90, v91
	v_or_b32_e32 v90, 32, v156
	v_ashrrev_i32_e32 v91, 31, v90
	v_lshlrev_b64 v[90:91], 7, v[90:91]
	v_lshl_add_u64 v[90:91], s[6:7], 0, v[90:91]
	v_lshl_add_u64 v[90:91], s[18:19], 2, v[90:91]
	s_lshl_b32 s4, s53, 2
	v_lshl_add_u64 v[90:91], v[90:91], 0, s[4:5]
	global_store_dword v[90:91], v92, off nt

.LBB0_951:
	s_or_b64 exec, exec, s[22:23]
	v_add_co_u32_e32 v66, vcc, 0x80000, v158
	s_add_u32 s22, s20, 0x80000
	s_waitcnt lgkmcnt(0)
	v_addc_co_u32_e32 v67, vcc, 0, v159, vcc
	global_load_dwordx4 v[74:77], v[66:67], off nt
	global_load_dwordx4 v[78:81], v[66:67], off offset:64 nt
	v_add_co_u32_e32 v66, vcc, 0x90000, v158
	s_addc_u32 s23, s21, 0
	s_nop 0
	v_addc_co_u32_e32 v67, vcc, 0, v159, vcc
	global_load_dwordx4 v[70:73], v[66:67], off nt
	s_nop 0
	global_load_dwordx4 v[66:69], v[66:67], off offset:64 nt
	s_waitcnt vmcnt(3)
	v_lshlrev_b32_e32 v82, 16, v74
	v_and_b32_e32 v74, 0xffff0000, v74
	v_add_f32_e32 v63, v63, v74
	v_lshlrev_b32_e32 v74, 16, v75
	v_add_f32_e32 v64, v64, v74
	v_and_b32_e32 v74, 0xffff0000, v75
	v_add_f32_e32 v65, v65, v74
	v_lshlrev_b32_e32 v74, 16, v76
	v_add_f32_e32 v74, v58, v74
	v_and_b32_e32 v58, 0xffff0000, v76
	v_add_f32_e32 v75, v59, v58
	v_lshlrev_b32_e32 v58, 16, v77
	v_add_f32_e32 v76, v60, v58
	v_and_b32_e32 v58, 0xffff0000, v77
	v_add_f32_e32 v62, v62, v82
	v_add_f32_e32 v77, v61, v58
	v_cvt_pk_bf16_f32 v58, v62, v63
	v_mul_f32_e32 v63, v63, v63
	v_fmac_f32_e32 v63, v62, v62
	v_mul_f32_e32 v62, v65, v65
	v_fmac_f32_e32 v62, v64, v64
	v_cvt_pk_bf16_f32 v59, v64, v65
	v_add_f32_e32 v62, v63, v62
	v_mul_f32_e32 v63, v75, v75
	v_mul_f32_e32 v64, v77, v77
	v_fmac_f32_e32 v63, v74, v74
	v_fmac_f32_e32 v64, v76, v76
	v_add_f32_e32 v63, v63, v64
	v_add_f32_e32 v62, v62, v63
	s_waitcnt vmcnt(2)
	v_lshlrev_b32_e32 v63, 16, v78
	v_add_f32_e32 v63, v54, v63
	v_and_b32_e32 v54, 0xffff0000, v78
	v_add_f32_e32 v55, v55, v54
	v_lshlrev_b32_e32 v54, 16, v79
	v_add_f32_e32 v56, v56, v54
	v_and_b32_e32 v54, 0xffff0000, v79
	v_add_f32_e32 v57, v57, v54
	v_lshlrev_b32_e32 v54, 16, v80
	v_add_f32_e32 v50, v50, v54
	v_and_b32_e32 v54, 0xffff0000, v80
	v_add_f32_e32 v64, v51, v54
	v_lshlrev_b32_e32 v51, 16, v81
	v_add_f32_e32 v65, v52, v51
	v_and_b32_e32 v51, 0xffff0000, v81
	v_cvt_pk_bf16_f32 v60, v74, v75
	v_cvt_pk_bf16_f32 v61, v76, v77
	v_add_f32_e32 v74, v53, v51
	v_cvt_pk_bf16_f32 v51, v63, v55
	v_cvt_pk_bf16_f32 v52, v56, v57
	v_mul_f32_e32 v57, v57, v57
	v_fmac_f32_e32 v57, v56, v56
	v_mul_f32_e32 v56, v64, v64
	v_cvt_pk_bf16_f32 v53, v50, v64
	v_mul_f32_e32 v55, v55, v55
	v_fmac_f32_e32 v56, v50, v50
	v_mul_f32_e32 v50, v74, v74
	v_fmac_f32_e32 v55, v63, v63
	v_fmac_f32_e32 v50, v65, v65
	v_add_f32_e32 v55, v55, v57
	v_add_f32_e32 v50, v56, v50
	v_add_f32_e32 v50, v55, v50
	v_add_f32_e32 v50, v62, v50
	v_cndmask_b32_e64 v62, v51, v58, s[36:37]
	v_mov_b32_e32 v63, v115
	v_cvt_pk_bf16_f32 v54, v65, v74
	v_cndmask_b32_e64 v56, v53, v60, s[36:37]
	v_cndmask_b32_e64 v55, v54, v61, s[36:37]
	v_cndmask_b32_e64 v57, v52, v59, s[36:37]
	v_mov_b32_dpp v63, v62 quad_perm:[1,0,3,2] row_mask:0xf bank_mask:0xf
	v_mov_b32_e32 v62, v115
	v_mov_b32_e32 v64, v115
	v_mov_b32_e32 v65, v115
	v_mov_b32_dpp v62, v57 quad_perm:[1,0,3,2] row_mask:0xf bank_mask:0xf
	v_mov_b32_dpp v64, v56 quad_perm:[1,0,3,2] row_mask:0xf bank_mask:0xf
	v_mov_b32_dpp v65, v55 quad_perm:[1,0,3,2] row_mask:0xf bank_mask:0xf
	v_cndmask_b32_e64 v56, v58, v63, s[36:37]
	v_cndmask_b32_e64 v57, v59, v62, s[36:37]
	v_cndmask_b32_e64 v58, v60, v64, s[36:37]
	v_cndmask_b32_e64 v59, v61, v65, s[36:37]
	v_lshl_add_u64 v[60:61], v[146:147], 1, s[22:23]
	global_store_dwordx4 v[60:61], v[56:59], off nt
	s_nop 1
	v_cndmask_b32_e64 v56, v63, v51, s[36:37]
	ds_bpermute_b32 v51, v116, v50
	v_cndmask_b32_e64 v57, v62, v52, s[36:37]
	v_cndmask_b32_e64 v58, v64, v53, s[36:37]
	v_cndmask_b32_e64 v59, v65, v54, s[36:37]
	v_lshl_add_u64 v[52:53], v[148:149], 1, s[22:23]
	s_waitcnt lgkmcnt(0)
	v_add_f32_e32 v50, v50, v51
	ds_bpermute_b32 v51, v117, v50
	global_store_dwordx4 v[52:53], v[56:59], off nt
	s_and_saveexec_b64 s[22:23], s[38:39]
	s_cbranch_execz .LBB0_953
	s_waitcnt lgkmcnt(0)
	v_add_f32_e32 v52, v50, v51
	v_lshlrev_b64 v[50:51], 7, v[156:157]
	v_lshl_add_u64 v[50:51], s[6:7], 0, v[50:51]
	v_lshl_add_u64 v[50:51], s[18:19], 2, v[50:51]
	s_lshl_b32 s4, s53, 2
	v_lshl_add_u64 v[50:51], v[50:51], 0, s[4:5]
	v_add_co_u32_e32 v50, vcc, 0x4000, v50
	s_nop 1
	v_addc_co_u32_e32 v51, vcc, 0, v51, vcc
	global_store_dword v[50:51], v52, off nt

.LBB0_955:
	s_or_b64 exec, exec, s[22:23]
	v_add_co_u32_e32 v34, vcc, 0xa0000, v158
	s_add_u32 s22, s20, 0xa0000
	s_waitcnt lgkmcnt(0)
	v_addc_co_u32_e32 v35, vcc, 0, v159, vcc
	global_load_dwordx4 v[42:45], v[34:35], off nt
	global_load_dwordx4 v[46:49], v[34:35], off offset:64 nt
	v_add_co_u32_e32 v34, vcc, 0xb0000, v158
	s_addc_u32 s23, s21, 0
	s_nop 0
	v_addc_co_u32_e32 v35, vcc, 0, v159, vcc
	global_load_dwordx4 v[38:41], v[34:35], off nt
	s_nop 0
	global_load_dwordx4 v[34:37], v[34:35], off offset:64 nt
	s_waitcnt vmcnt(3)
	v_lshlrev_b32_e32 v50, 16, v42
	v_and_b32_e32 v42, 0xffff0000, v42
	v_add_f32_e32 v31, v31, v42
	v_lshlrev_b32_e32 v42, 16, v43
	v_add_f32_e32 v32, v32, v42
	v_and_b32_e32 v42, 0xffff0000, v43
	v_add_f32_e32 v33, v33, v42
	v_lshlrev_b32_e32 v42, 16, v44
	v_add_f32_e32 v42, v26, v42
	v_and_b32_e32 v26, 0xffff0000, v44
	v_add_f32_e32 v43, v27, v26
	v_lshlrev_b32_e32 v26, 16, v45
	v_add_f32_e32 v44, v28, v26
	v_and_b32_e32 v26, 0xffff0000, v45
	v_add_f32_e32 v30, v30, v50
	v_add_f32_e32 v45, v29, v26
	v_cvt_pk_bf16_f32 v26, v30, v31
	v_mul_f32_e32 v31, v31, v31
	v_fmac_f32_e32 v31, v30, v30
	v_mul_f32_e32 v30, v33, v33
	v_fmac_f32_e32 v30, v32, v32
	v_cvt_pk_bf16_f32 v27, v32, v33
	v_add_f32_e32 v30, v31, v30
	v_mul_f32_e32 v31, v43, v43
	v_mul_f32_e32 v32, v45, v45
	v_fmac_f32_e32 v31, v42, v42
	v_fmac_f32_e32 v32, v44, v44
	v_add_f32_e32 v31, v31, v32
	v_add_f32_e32 v30, v30, v31
	s_waitcnt vmcnt(2)
	v_lshlrev_b32_e32 v31, 16, v46
	v_add_f32_e32 v31, v22, v31
	v_and_b32_e32 v22, 0xffff0000, v46
	v_add_f32_e32 v23, v23, v22
	v_lshlrev_b32_e32 v22, 16, v47
	v_add_f32_e32 v24, v24, v22
	v_and_b32_e32 v22, 0xffff0000, v47
	v_add_f32_e32 v25, v25, v22
	v_lshlrev_b32_e32 v22, 16, v48
	v_add_f32_e32 v18, v18, v22
	v_and_b32_e32 v22, 0xffff0000, v48
	v_add_f32_e32 v32, v19, v22
	v_lshlrev_b32_e32 v19, 16, v49
	v_add_f32_e32 v33, v20, v19
	v_and_b32_e32 v19, 0xffff0000, v49
	v_cvt_pk_bf16_f32 v28, v42, v43
	v_cvt_pk_bf16_f32 v29, v44, v45
	v_add_f32_e32 v42, v21, v19
	v_cvt_pk_bf16_f32 v19, v31, v23
	v_cvt_pk_bf16_f32 v20, v24, v25
	v_mul_f32_e32 v25, v25, v25
	v_fmac_f32_e32 v25, v24, v24
	v_mul_f32_e32 v24, v32, v32
	v_cvt_pk_bf16_f32 v21, v18, v32
	v_mul_f32_e32 v23, v23, v23
	v_fmac_f32_e32 v24, v18, v18
	v_mul_f32_e32 v18, v42, v42
	v_fmac_f32_e32 v23, v31, v31
	v_fmac_f32_e32 v18, v33, v33
	v_add_f32_e32 v23, v23, v25
	v_add_f32_e32 v18, v24, v18
	v_add_f32_e32 v18, v23, v18
	v_add_f32_e32 v18, v30, v18
	v_cndmask_b32_e64 v30, v19, v26, s[36:37]
	v_mov_b32_e32 v31, v115
	v_cvt_pk_bf16_f32 v22, v33, v42
	v_cndmask_b32_e64 v24, v21, v28, s[36:37]
	v_cndmask_b32_e64 v23, v22, v29, s[36:37]
	v_cndmask_b32_e64 v25, v20, v27, s[36:37]
	v_mov_b32_dpp v31, v30 quad_perm:[1,0,3,2] row_mask:0xf bank_mask:0xf
	v_mov_b32_e32 v30, v115
	v_mov_b32_e32 v32, v115
	v_mov_b32_e32 v33, v115
	v_mov_b32_dpp v30, v25 quad_perm:[1,0,3,2] row_mask:0xf bank_mask:0xf
	v_mov_b32_dpp v32, v24 quad_perm:[1,0,3,2] row_mask:0xf bank_mask:0xf
	v_mov_b32_dpp v33, v23 quad_perm:[1,0,3,2] row_mask:0xf bank_mask:0xf
	v_cndmask_b32_e64 v24, v26, v31, s[36:37]
	v_cndmask_b32_e64 v25, v27, v30, s[36:37]
	v_cndmask_b32_e64 v26, v28, v32, s[36:37]
	v_cndmask_b32_e64 v27, v29, v33, s[36:37]
	v_lshl_add_u64 v[28:29], v[146:147], 1, s[22:23]
	global_store_dwordx4 v[28:29], v[24:27], off nt
	s_nop 1
	v_cndmask_b32_e64 v24, v31, v19, s[36:37]
	ds_bpermute_b32 v19, v116, v18
	v_cndmask_b32_e64 v25, v30, v20, s[36:37]
	v_cndmask_b32_e64 v26, v32, v21, s[36:37]
	v_cndmask_b32_e64 v27, v33, v22, s[36:37]
	v_lshl_add_u64 v[20:21], v[148:149], 1, s[22:23]
	s_waitcnt lgkmcnt(0)
	v_add_f32_e32 v18, v18, v19
	ds_bpermute_b32 v19, v117, v18
	global_store_dwordx4 v[20:21], v[24:27], off nt
	s_and_saveexec_b64 s[22:23], s[38:39]
	s_cbranch_execz .LBB0_957
	s_waitcnt lgkmcnt(0)
	v_add_f32_e32 v20, v18, v19
	v_lshlrev_b64 v[18:19], 7, v[156:157]
	v_lshl_add_u64 v[18:19], s[6:7], 0, v[18:19]
	v_lshl_add_u64 v[18:19], s[18:19], 2, v[18:19]
	s_lshl_b32 s4, s53, 2
	v_lshl_add_u64 v[18:19], v[18:19], 0, s[4:5]
	v_add_co_u32_e32 v18, vcc, 0x5000, v18
	s_nop 1
	v_addc_co_u32_e32 v19, vcc, 0, v19, vcc
	global_store_dword v[18:19], v20, off nt

.LBB0_1025:
	global_load_dwordx4 v[14:17], v[20:21], off offset:-2048 nt
	global_load_dwordx4 v[10:13], v[20:21], off offset:-1024 nt
	global_load_dwordx4 v[6:9], v[20:21], off nt
	global_load_dwordx4 v[2:5], v[20:21], off offset:1024 nt
	v_mov_b32_e32 v49, 0
	s_and_saveexec_b64 s[20:21], s[36:37]
	s_cbranch_execz .LBB0_1027
	global_load_dword v49, v[18:19], off

.LBB0_1034:
	s_ashr_i32 s13, s25, 4
	s_lshl_b32 s14, s13, 8
	s_lshl_b32 s12, s13, 7
	s_and_b32 s15, s4, 0x780
	s_add_i32 s16, s14, 0xffffd420
	s_cmp_lt_i32 s13, 44
	s_cselect_b32 s14, s14, s16
	s_ashr_i32 s13, s12, 31
	s_lshl_b64 s[12:13], s[12:13], 2
	v_lshl_add_u64 v[2:3], v[6:7], 0, s[12:13]
	global_load_dwordx4 v[2:5], v[2:3], off nt
	v_add_u32_e32 v14, s15, v43
	v_lshl_add_u64 v[12:13], v[8:9], 0, s[12:13]
	v_ashrrev_i32_e32 v15, 31, v14
	s_waitcnt vmcnt(0)
	v_max_f32_e32 v2, v2, v2
	v_max_f32_e32 v2, 0xda24260, v2
	v_div_scale_f32 v3, s[16:17], v2, v2, s47
	v_rcp_f32_e32 v4, v3
	s_nop 0
	v_fma_f32 v5, -v3, v4, 1.0
	v_fmac_f32_e32 v4, v5, v4
	v_div_scale_f32 v5, vcc, s47, v2, s47
	v_mul_f32_e32 v10, v5, v4
	v_fma_f32 v11, -v3, v10, v5
	v_fmac_f32_e32 v10, v11, v4
	v_fma_f32 v3, -v3, v10, v5
	v_div_fmas_f32 v3, v3, v4, v10
	v_div_fixup_f32 v10, v3, v2, s47
	v_mad_i64_i32 v[2:3], s[12:13], v14, s18, v[12:13]
	v_lshl_add_u64 v[14:15], v[14:15], 2, s[10:11]
	global_load_dwordx4 v[2:5], v[2:3], off nt
	s_nop 0
	global_load_dword v14, v[14:15], off
	s_waitcnt vmcnt(0)
	v_pk_mul_f32 v[2:3], v[2:3], v[14:15] op_sel_hi:[1,0]
	v_pk_mul_f32 v[4:5], v[4:5], v[14:15] op_sel_hi:[1,0]
	v_add_u32_e32 v14, s15, v44
	v_pk_mul_f32 v[2:3], v[10:11], v[2:3] op_sel_hi:[0,1]
	v_ashrrev_i32_e32 v15, 31, v14
	v_pk_mul_f32 v[4:5], v[10:11], v[4:5] op_sel_hi:[0,1]
	ds_write2_b32 v55, v2, v3 offset1:1
	ds_write2_b32 v55, v4, v5 offset0:2 offset1:3
	v_mad_i64_i32 v[2:3], s[12:13], v14, s18, v[12:13]
	v_lshl_add_u64 v[14:15], v[14:15], 2, s[10:11]
	global_load_dwordx4 v[2:5], v[2:3], off nt
	s_nop 0
	global_load_dword v14, v[14:15], off
	s_waitcnt vmcnt(0)
	v_pk_mul_f32 v[2:3], v[2:3], v[14:15] op_sel_hi:[1,0]
	v_pk_mul_f32 v[4:5], v[4:5], v[14:15] op_sel_hi:[1,0]
	v_add_u32_e32 v14, s15, v45
	v_pk_mul_f32 v[2:3], v[10:11], v[2:3] op_sel_hi:[0,1]
	v_ashrrev_i32_e32 v15, 31, v14
	v_pk_mul_f32 v[4:5], v[10:11], v[4:5] op_sel_hi:[0,1]
	ds_write2_b32 v56, v2, v3 offset1:1
	ds_write2_b32 v56, v4, v5 offset0:2 offset1:3
	v_mad_i64_i32 v[2:3], s[12:13], v14, s18, v[12:13]
	v_lshl_add_u64 v[14:15], v[14:15], 2, s[10:11]
	global_load_dwordx4 v[2:5], v[2:3], off nt
	s_nop 0
	global_load_dword v14, v[14:15], off
	s_waitcnt vmcnt(0)
	v_pk_mul_f32 v[2:3], v[2:3], v[14:15] op_sel_hi:[1,0]
	v_pk_mul_f32 v[4:5], v[4:5], v[14:15] op_sel_hi:[1,0]
	v_add_u32_e32 v14, s15, v46
	v_pk_mul_f32 v[2:3], v[10:11], v[2:3] op_sel_hi:[0,1]
	v_ashrrev_i32_e32 v15, 31, v14
	v_pk_mul_f32 v[4:5], v[10:11], v[4:5] op_sel_hi:[0,1]
	ds_write2_b32 v57, v2, v3 offset1:1
	ds_write2_b32 v57, v4, v5 offset0:2 offset1:3
	v_mad_i64_i32 v[2:3], s[12:13], v14, s18, v[12:13]
	v_lshl_add_u64 v[14:15], v[14:15], 2, s[10:11]
	global_load_dwordx4 v[2:5], v[2:3], off nt
	s_nop 0
	global_load_dword v14, v[14:15], off
	s_waitcnt vmcnt(0)
	v_pk_mul_f32 v[2:3], v[2:3], v[14:15] op_sel_hi:[1,0]
	v_pk_mul_f32 v[4:5], v[4:5], v[14:15] op_sel_hi:[1,0]
	v_add_u32_e32 v14, s15, v47
	v_pk_mul_f32 v[2:3], v[10:11], v[2:3] op_sel_hi:[0,1]
	v_ashrrev_i32_e32 v15, 31, v14
	v_pk_mul_f32 v[4:5], v[10:11], v[4:5] op_sel_hi:[0,1]
	ds_write2_b32 v58, v2, v3 offset1:1
	ds_write2_b32 v58, v4, v5 offset0:2 offset1:3
	v_mad_i64_i32 v[2:3], s[12:13], v14, s18, v[12:13]
	v_lshl_add_u64 v[14:15], v[14:15], 2, s[10:11]
	global_load_dwordx4 v[2:5], v[2:3], off nt
	s_nop 0
	global_load_dword v14, v[14:15], off
	s_waitcnt vmcnt(0)
	v_pk_mul_f32 v[2:3], v[2:3], v[14:15] op_sel_hi:[1,0]
	v_pk_mul_f32 v[4:5], v[4:5], v[14:15] op_sel_hi:[1,0]
	v_add_u32_e32 v14, s15, v48
	v_pk_mul_f32 v[2:3], v[10:11], v[2:3] op_sel_hi:[0,1]
	v_ashrrev_i32_e32 v15, 31, v14
	v_pk_mul_f32 v[4:5], v[10:11], v[4:5] op_sel_hi:[0,1]
	ds_write2_b32 v59, v2, v3 offset1:1
	ds_write2_b32 v59, v4, v5 offset0:2 offset1:3
	v_mad_i64_i32 v[2:3], s[12:13], v14, s18, v[12:13]
	v_lshl_add_u64 v[14:15], v[14:15], 2, s[10:11]
	global_load_dwordx4 v[2:5], v[2:3], off nt
	s_nop 0
	global_load_dword v14, v[14:15], off
	s_waitcnt vmcnt(0)
	v_pk_mul_f32 v[2:3], v[2:3], v[14:15] op_sel_hi:[1,0]
	v_pk_mul_f32 v[4:5], v[4:5], v[14:15] op_sel_hi:[1,0]
	v_add_u32_e32 v14, s15, v49
	v_pk_mul_f32 v[2:3], v[10:11], v[2:3] op_sel_hi:[0,1]
	v_ashrrev_i32_e32 v15, 31, v14
	v_pk_mul_f32 v[4:5], v[10:11], v[4:5] op_sel_hi:[0,1]
	ds_write2_b32 v60, v2, v3 offset1:1
	ds_write2_b32 v60, v4, v5 offset0:2 offset1:3
	v_mad_i64_i32 v[2:3], s[12:13], v14, s18, v[12:13]
	v_lshl_add_u64 v[14:15], v[14:15], 2, s[10:11]
	global_load_dwordx4 v[2:5], v[2:3], off nt
	s_nop 0
	global_load_dword v14, v[14:15], off
	s_waitcnt vmcnt(0)
	v_pk_mul_f32 v[2:3], v[2:3], v[14:15] op_sel_hi:[1,0]
	v_pk_mul_f32 v[4:5], v[4:5], v[14:15] op_sel_hi:[1,0]
	v_add_u32_e32 v14, s15, v50
	v_pk_mul_f32 v[2:3], v[10:11], v[2:3] op_sel_hi:[0,1]
	v_ashrrev_i32_e32 v15, 31, v14
	v_pk_mul_f32 v[4:5], v[10:11], v[4:5] op_sel_hi:[0,1]
	ds_write2_b32 v61, v2, v3 offset1:1
	ds_write2_b32 v61, v4, v5 offset0:2 offset1:3
	v_mad_i64_i32 v[2:3], s[12:13], v14, s18, v[12:13]
	v_lshl_add_u64 v[12:13], v[14:15], 2, s[10:11]
	global_load_dwordx4 v[2:5], v[2:3], off nt
	s_add_u32 s12, s1, s15
	global_load_dword v12, v[12:13], off
	s_addc_u32 s13, s3, 0
	s_add_i32 s25, s25, s24
	s_add_i32 s4, s4, s7
	s_cmpk_gt_i32 s25, 0x57f
	s_waitcnt vmcnt(0)
	v_pk_mul_f32 v[2:3], v[2:3], v[12:13] op_sel_hi:[1,0]
	v_pk_mul_f32 v[4:5], v[4:5], v[12:13] op_sel_hi:[1,0]
	v_pk_mul_f32 v[2:3], v[10:11], v[2:3] op_sel_hi:[0,1]
	v_pk_mul_f32 v[4:5], v[10:11], v[4:5] op_sel_hi:[0,1]
	ds_write2_b32 v62, v2, v3 offset1:1
	ds_write2_b32 v62, v4, v5 offset0:2 offset1:3
	s_waitcnt lgkmcnt(0)
	s_barrier
	ds_read2_b32 v[12:13], v51 offset0:129 offset1:193
	ds_read2st64_b32 v[10:11], v51 offset1:1
	v_add_u32_e32 v4, 12, v51
	ds_read2st64_b32 v[16:17], v4 offset0:6 offset1:7
	v_add_u32_e32 v5, 28, v51
	s_waitcnt lgkmcnt(2)
	v_rndne_f32_e32 v3, v12
	s_waitcnt lgkmcnt(1)
	v_rndne_f32_e32 v2, v10
	v_cvt_i32_f32_e32 v3, v3
	v_cvt_i32_f32_e32 v2, v2
	s_waitcnt lgkmcnt(0)
	v_rndne_f32_e32 v4, v16
	v_cvt_i32_f32_e32 v4, v4
	v_med3_i32 v3, v3, s71, v235
	v_med3_i32 v2, v2, s71, v235
	v_lshlrev_b32_e32 v3, 8, v3
	v_perm_b32 v2, v3, v2, s49
	v_add_u32_e32 v3, 8, v51
	ds_read2st64_b32 v[14:15], v3 offset0:4 offset1:5
	v_med3_i32 v4, v4, s71, v235
	v_lshlrev_b32_e32 v4, 24, v4
	ds_read2st64_b32 v[24:25], v5 offset0:14 offset1:15
	v_add_u32_e32 v10, 44, v51
	s_waitcnt lgkmcnt(1)
	v_rndne_f32_e32 v3, v14
	v_cvt_i32_f32_e32 v3, v3
	ds_read2st64_b32 v[32:33], v10 offset0:22 offset1:23
	s_waitcnt lgkmcnt(1)
	v_rndne_f32_e32 v5, v24
	v_cvt_i32_f32_e32 v5, v5
	v_med3_i32 v3, v3, s71, v235
	v_lshlrev_b32_e32 v3, 16, v3
	v_and_b32_e32 v3, 0xff0000, v3
	v_or3_b32 v2, v2, v3, v4
	v_add_u32_e32 v4, 20, v51
	v_add_u32_e32 v3, 16, v51
	ds_read2st64_b32 v[20:21], v4 offset0:10 offset1:11
	ds_read2st64_b32 v[18:19], v3 offset0:8 offset1:9
	v_med3_i32 v5, v5, s71, v235
	v_lshlrev_b32_e32 v5, 24, v5
	s_waitcnt lgkmcnt(2)
	v_rndne_f32_e32 v10, v32
	s_waitcnt lgkmcnt(1)
	v_rndne_f32_e32 v4, v20
	s_waitcnt lgkmcnt(0)
	v_rndne_f32_e32 v3, v18
	v_cvt_i32_f32_e32 v4, v4
	v_cvt_i32_f32_e32 v3, v3
	v_cvt_i32_f32_e32 v10, v10
	v_add_u32_e32 v12, 60, v51
	v_med3_i32 v4, v4, s71, v235
	v_med3_i32 v3, v3, s71, v235
	v_lshlrev_b32_e32 v4, 8, v4
	v_perm_b32 v3, v4, v3, s49
	v_add_u32_e32 v4, 24, v51
	ds_read2st64_b32 v[22:23], v4 offset0:12 offset1:13
	v_med3_i32 v10, v10, s71, v235
	v_lshlrev_b32_e32 v10, 24, v10
	ds_read2st64_b32 v[40:41], v12 offset0:30 offset1:31
	s_waitcnt lgkmcnt(1)
	v_rndne_f32_e32 v4, v22
	v_cvt_i32_f32_e32 v4, v4
	s_waitcnt lgkmcnt(0)
	v_rndne_f32_e32 v12, v40
	v_cvt_i32_f32_e32 v12, v12
	v_med3_i32 v4, v4, s71, v235
	v_lshlrev_b32_e32 v4, 16, v4
	v_and_b32_e32 v4, 0xff0000, v4
	v_or3_b32 v3, v3, v4, v5
	v_add_u32_e32 v5, 36, v51
	v_add_u32_e32 v4, 32, v51
	ds_read2st64_b32 v[28:29], v5 offset0:18 offset1:19
	ds_read2st64_b32 v[26:27], v4 offset0:16 offset1:17
	v_med3_i32 v12, v12, s71, v235
	v_lshlrev_b32_e32 v12, 24, v12
	s_waitcnt lgkmcnt(1)
	v_rndne_f32_e32 v5, v28
	s_waitcnt lgkmcnt(0)
	v_rndne_f32_e32 v4, v26
	v_cvt_i32_f32_e32 v5, v5
	v_cvt_i32_f32_e32 v4, v4
	v_med3_i32 v5, v5, s71, v235
	v_med3_i32 v4, v4, s71, v235
	v_lshlrev_b32_e32 v5, 8, v5
	v_perm_b32 v4, v5, v4, s49
	v_add_u32_e32 v5, 40, v51
	ds_read2st64_b32 v[30:31], v5 offset0:20 offset1:21
	s_waitcnt lgkmcnt(0)
	v_rndne_f32_e32 v5, v30
	v_cvt_i32_f32_e32 v5, v5
	v_med3_i32 v5, v5, s71, v235
	v_lshlrev_b32_e32 v5, 16, v5
	v_and_b32_e32 v5, 0xff0000, v5
	v_or3_b32 v4, v4, v5, v10
	v_add_u32_e32 v10, 52, v51
	v_add_u32_e32 v5, 48, v51
	ds_read2st64_b32 v[36:37], v10 offset0:26 offset1:27
	ds_read2st64_b32 v[34:35], v5 offset0:24 offset1:25
	s_waitcnt lgkmcnt(1)
	v_rndne_f32_e32 v10, v36
	s_waitcnt lgkmcnt(0)
	v_rndne_f32_e32 v5, v34
	v_cvt_i32_f32_e32 v10, v10
	v_cvt_i32_f32_e32 v5, v5
	v_med3_i32 v10, v10, s71, v235
	v_med3_i32 v5, v5, s71, v235
	v_lshlrev_b32_e32 v10, 8, v10
	v_perm_b32 v5, v10, v5, s49
	v_add_u32_e32 v10, 56, v51
	ds_read2st64_b32 v[38:39], v10 offset0:28 offset1:29
	s_waitcnt lgkmcnt(0)
	v_rndne_f32_e32 v10, v38
	v_cvt_i32_f32_e32 v10, v10
	v_med3_i32 v10, v10, s71, v235
	v_lshlrev_b32_e32 v10, 16, v10
	v_and_b32_e32 v10, 0xff0000, v10
	v_or3_b32 v5, v5, v10, v12
	v_or_b32_e32 v10, s14, v53
	v_add_u32_e32 v64, v10, v52
	v_ashrrev_i32_e32 v65, 31, v64
	v_lshlrev_b64 v[64:65], 11, v[64:65]
	v_lshl_add_u64 v[64:65], s[12:13], 0, v[64:65]
	v_lshl_add_u64 v[64:65], v[64:65], 0, v[114:115]
	global_store_dwordx4 v[64:65], v[2:5], off
	v_rndne_f32_e32 v12, v41
	v_cvt_i32_f32_e32 v12, v12
	v_rndne_f32_e32 v3, v13
	v_rndne_f32_e32 v2, v11
	v_cvt_i32_f32_e32 v3, v3
	v_cvt_i32_f32_e32 v2, v2
	v_rndne_f32_e32 v4, v17
	v_cvt_i32_f32_e32 v4, v4
	v_med3_i32 v3, v3, s71, v235
	v_med3_i32 v2, v2, s71, v235
	v_lshlrev_b32_e32 v3, 8, v3
	v_perm_b32 v2, v3, v2, s49
	v_rndne_f32_e32 v3, v15
	v_cvt_i32_f32_e32 v3, v3
	v_med3_i32 v4, v4, s71, v235
	v_lshlrev_b32_e32 v4, 24, v4
	v_rndne_f32_e32 v5, v25
	v_med3_i32 v3, v3, s71, v235
	v_lshlrev_b32_e32 v3, 16, v3
	v_and_b32_e32 v3, 0xff0000, v3
	v_or3_b32 v2, v2, v3, v4
	v_rndne_f32_e32 v4, v21
	v_rndne_f32_e32 v3, v19
	v_cvt_i32_f32_e32 v4, v4
	v_cvt_i32_f32_e32 v3, v3
	v_cvt_i32_f32_e32 v5, v5
	v_rndne_f32_e32 v11, v33
	v_med3_i32 v4, v4, s71, v235
	v_med3_i32 v3, v3, s71, v235
	v_lshlrev_b32_e32 v4, 8, v4
	v_perm_b32 v3, v4, v3, s49
	v_rndne_f32_e32 v4, v23
	v_cvt_i32_f32_e32 v4, v4
	v_med3_i32 v5, v5, s71, v235
	v_lshlrev_b32_e32 v5, 24, v5
	v_cvt_i32_f32_e32 v11, v11
	v_med3_i32 v4, v4, s71, v235
	v_lshlrev_b32_e32 v4, 16, v4
	v_and_b32_e32 v4, 0xff0000, v4
	v_or3_b32 v3, v3, v4, v5
	v_rndne_f32_e32 v5, v29
	v_rndne_f32_e32 v4, v27
	v_cvt_i32_f32_e32 v5, v5
	v_cvt_i32_f32_e32 v4, v4
	v_med3_i32 v11, v11, s71, v235
	v_lshlrev_b32_e32 v11, 24, v11
	v_med3_i32 v5, v5, s71, v235
	v_med3_i32 v4, v4, s71, v235
	v_lshlrev_b32_e32 v5, 8, v5
	v_perm_b32 v4, v5, v4, s49
	v_rndne_f32_e32 v5, v31
	v_cvt_i32_f32_e32 v5, v5
	v_med3_i32 v12, v12, s71, v235
	v_lshlrev_b32_e32 v12, 24, v12
	v_add_u32_e32 v10, v10, v54
	v_med3_i32 v5, v5, s71, v235
	v_lshlrev_b32_e32 v5, 16, v5
	v_and_b32_e32 v5, 0xff0000, v5
	v_or3_b32 v4, v4, v5, v11
	v_rndne_f32_e32 v11, v37
	v_rndne_f32_e32 v5, v35
	v_cvt_i32_f32_e32 v11, v11
	v_cvt_i32_f32_e32 v5, v5
	v_med3_i32 v11, v11, s71, v235
	v_med3_i32 v5, v5, s71, v235
	v_lshlrev_b32_e32 v11, 8, v11
	v_perm_b32 v5, v11, v5, s49
	v_rndne_f32_e32 v11, v39
	v_cvt_i32_f32_e32 v11, v11
	v_med3_i32 v11, v11, s71, v235
	v_lshlrev_b32_e32 v11, 16, v11
	v_and_b32_e32 v11, 0xff0000, v11
	v_or3_b32 v5, v5, v11, v12
	v_ashrrev_i32_e32 v11, 31, v10
	v_lshlrev_b64 v[10:11], 11, v[10:11]
	v_lshl_add_u64 v[10:11], s[12:13], 0, v[10:11]
	v_lshl_add_u64 v[10:11], v[10:11], 0, v[114:115]
	global_store_dwordx4 v[10:11], v[2:5], off
	s_barrier
	s_cbranch_scc0 .LBB0_1034

.LBB0_1038:
	global_load_dwordx4 v[14:17], v[20:21], off offset:-2048 nt
	global_load_dwordx4 v[10:13], v[20:21], off offset:-1024 nt
	global_load_dwordx4 v[6:9], v[20:21], off nt
	global_load_dwordx4 v[2:5], v[20:21], off offset:1024 nt
	v_mov_b32_e32 v47, 0
	s_and_saveexec_b64 s[6:7], s[36:37]
	s_cbranch_execz .LBB0_1040
	global_load_dword v47, v[18:19], off

.LBB0_1272:
	global_load_dwordx4 v[182:185], v[174:175], off nt
	global_load_dwordx4 v[186:189], v[174:175], off offset:64 nt
	v_add_co_u32_e32 v132, vcc, 0x10000, v174
	v_mov_b32_e32 v191, v115
	s_nop 0
	v_addc_co_u32_e32 v133, vcc, 0, v175, vcc
	global_load_dwordx4 v[136:139], v[132:133], off nt
	s_nop 0
	global_load_dwordx4 v[132:135], v[132:133], off offset:64 nt
	v_mov_b32_e32 v177, v115
	s_add_u32 s20, s90, s20
	v_mov_b32_e32 v190, v115
	s_addc_u32 s21, s91, s21
	v_add_u32_e32 v176, s22, v178
	s_lshl_b32 s22, s3, 2
	s_ashr_i32 s23, s22, 31
	s_waitcnt vmcnt(0)
	v_lshlrev_b32_e32 v160, 16, v182
	v_and_b32_e32 v161, 0xffff0000, v182
	v_lshlrev_b32_e32 v181, 16, v183
	v_and_b32_e32 v182, 0xffff0000, v183
	v_lshlrev_b32_e32 v183, 16, v184
	v_and_b32_e32 v184, 0xffff0000, v184
	v_lshlrev_b32_e32 v192, 16, v185
	v_and_b32_e32 v185, 0xffff0000, v185
	v_lshlrev_b32_e32 v193, 16, v186
	v_and_b32_e32 v186, 0xffff0000, v186
	v_lshlrev_b32_e32 v194, 16, v187
	v_and_b32_e32 v187, 0xffff0000, v187
	v_lshlrev_b32_e32 v195, 16, v188
	v_and_b32_e32 v188, 0xffff0000, v188
	v_lshlrev_b32_e32 v196, 16, v189
	v_and_b32_e32 v189, 0xffff0000, v189
	v_add_f32_e32 v161, v129, v161
	v_add_f32_e32 v182, v131, v182
	v_add_f32_e32 v184, v125, v184
	v_add_f32_e32 v185, v127, v185
	v_add_f32_e32 v186, v121, v186
	v_add_f32_e32 v187, v123, v187
	v_add_f32_e32 v188, v117, v188
	v_add_f32_e32 v189, v119, v189
	v_add_f32_e32 v160, v128, v160
	v_add_f32_e32 v181, v130, v181
	v_add_f32_e32 v183, v124, v183
	v_add_f32_e32 v192, v126, v192
	v_add_f32_e32 v193, v120, v193
	v_add_f32_e32 v194, v122, v194
	v_add_f32_e32 v195, v116, v195
	v_add_f32_e32 v196, v118, v196
	v_cvt_pk_bf16_f32 v197, v160, v161
	v_cvt_pk_bf16_f32 v198, v181, v182
	v_cvt_pk_bf16_f32 v199, v183, v184
	v_cvt_pk_bf16_f32 v200, v192, v185
	v_mul_f32_e32 v161, v161, v161
	v_mul_f32_e32 v182, v182, v182
	v_mul_f32_e32 v184, v184, v184
	v_mul_f32_e32 v185, v185, v185
	v_cvt_pk_bf16_f32 v201, v193, v186
	v_cvt_pk_bf16_f32 v202, v194, v187
	v_cvt_pk_bf16_f32 v203, v195, v188
	v_cvt_pk_bf16_f32 v204, v196, v189
	v_mul_f32_e32 v186, v186, v186
	v_mul_f32_e32 v187, v187, v187
	v_mul_f32_e32 v188, v188, v188
	v_mul_f32_e32 v189, v189, v189
	v_fmac_f32_e32 v161, v160, v160
	v_fmac_f32_e32 v182, v181, v181
	v_fmac_f32_e32 v184, v183, v183
	v_fmac_f32_e32 v185, v192, v192
	v_fmac_f32_e32 v186, v193, v193
	v_fmac_f32_e32 v187, v194, v194
	v_fmac_f32_e32 v188, v195, v195
	v_fmac_f32_e32 v189, v196, v196
	v_cndmask_b32_e64 v181, v203, v199, s[36:37]
	v_add_f32_e32 v161, v161, v182
	v_add_f32_e32 v182, v184, v185
	v_add_f32_e32 v184, v186, v187
	v_add_f32_e32 v185, v188, v189
	v_mov_b32_dpp v191, v181 quad_perm:[1,0,3,2] row_mask:0xf bank_mask:0xf
	v_add_f32_e32 v161, v161, v182
	v_add_f32_e32 v181, v184, v185
	v_and_b32_e32 v186, 64, v234
	v_add_f32_e32 v189, v161, v181
	v_xor_b32_e32 v181, 16, v234
	v_add_u32_e32 v193, 64, v186
	v_cmp_lt_i32_e32 vcc, v181, v193
	v_cndmask_b32_e64 v192, v201, v197, s[36:37]
	v_cndmask_b32_e64 v160, v204, v200, s[36:37]
	v_cndmask_b32_e32 v181, v234, v181, vcc
	v_cndmask_b32_e64 v183, v202, v198, s[36:37]
	v_mov_b32_dpp v177, v192 quad_perm:[1,0,3,2] row_mask:0xf bank_mask:0xf
	v_mov_b32_e32 v192, v115
	v_lshlrev_b32_e32 v181, 2, v181
	v_mov_b32_dpp v190, v183 quad_perm:[1,0,3,2] row_mask:0xf bank_mask:0xf
	v_mov_b32_dpp v192, v160 quad_perm:[1,0,3,2] row_mask:0xf bank_mask:0xf
	ds_bpermute_b32 v194, v181, v189
	v_cndmask_b32_e64 v182, v197, v177, s[36:37]
	v_cndmask_b32_e64 v183, v198, v190, s[36:37]
	v_cndmask_b32_e64 v184, v199, v191, s[36:37]
	v_cndmask_b32_e64 v185, v200, v192, s[36:37]
	v_lshl_add_u64 v[160:161], v[148:149], 1, s[20:21]
	global_store_dwordx4 v[160:161], v[182:185], off nt
	v_xor_b32_e32 v160, 32, v234
	v_cmp_lt_i32_e32 vcc, v160, v193
	s_waitcnt lgkmcnt(0)
	v_add_f32_e32 v183, v189, v194
	v_cndmask_b32_e64 v186, v177, v201, s[36:37]
	v_cndmask_b32_e32 v160, v234, v160, vcc
	v_lshlrev_b32_e32 v182, 2, v160
	ds_bpermute_b32 v184, v182, v183
	v_cndmask_b32_e64 v187, v190, v202, s[36:37]
	v_cndmask_b32_e64 v188, v191, v203, s[36:37]
	v_cndmask_b32_e64 v189, v192, v204, s[36:37]
	v_lshl_add_u64 v[160:161], v[150:151], 1, s[20:21]
	v_ashrrev_i32_e32 v177, 31, v176
	global_store_dwordx4 v[160:161], v[186:189], off nt
	s_and_saveexec_b64 s[24:25], s[38:39]
	s_cbranch_execz .LBB0_1274
	v_lshlrev_b64 v[160:161], 7, v[176:177]
	v_lshl_add_u64 v[160:161], s[6:7], 0, v[160:161]
	v_lshl_add_u64 v[160:161], s[22:23], 2, v[160:161]
	s_lshl_b32 s4, s53, 2
	v_lshl_add_u64 v[160:161], v[160:161], 0, s[4:5]
	s_waitcnt lgkmcnt(0)
	v_add_f32_e32 v183, v183, v184
	global_store_dword v[160:161], v183, off nt

.LBB0_1276:
	s_or_b64 exec, exec, s[24:25]
	v_add_co_u32_e32 v132, vcc, 0x20000, v174
	s_add_u32 s24, s20, 0x20000
	s_waitcnt lgkmcnt(0)
	v_addc_co_u32_e32 v133, vcc, 0, v175, vcc
	global_load_dwordx4 v[184:187], v[132:133], off nt
	global_load_dwordx4 v[188:191], v[132:133], off offset:64 nt
	v_add_co_u32_e32 v132, vcc, 0x30000, v174
	s_addc_u32 s25, s21, 0
	s_nop 0
	v_addc_co_u32_e32 v133, vcc, 0, v175, vcc
	global_load_dwordx4 v[136:139], v[132:133], off nt
	s_nop 0
	global_load_dwordx4 v[132:135], v[132:133], off offset:64 nt
	s_waitcnt vmcnt(3)
	v_lshlrev_b32_e32 v160, 16, v184
	v_and_b32_e32 v161, 0xffff0000, v184
	v_and_b32_e32 v184, 0xffff0000, v185
	v_add_f32_e32 v192, v97, v184
	v_lshlrev_b32_e32 v184, 16, v186
	v_add_f32_e32 v193, v90, v184
	v_and_b32_e32 v184, 0xffff0000, v186
	v_add_f32_e32 v194, v91, v184
	v_lshlrev_b32_e32 v184, 16, v187
	v_add_f32_e32 v161, v95, v161
	v_add_f32_e32 v195, v92, v184
	v_and_b32_e32 v184, 0xffff0000, v187
	v_add_f32_e32 v160, v94, v160
	v_lshlrev_b32_e32 v183, 16, v185
	v_add_f32_e32 v196, v93, v184
	v_cvt_pk_bf16_f32 v184, v160, v161
	v_mul_f32_e32 v161, v161, v161
	v_add_f32_e32 v183, v96, v183
	v_fmac_f32_e32 v161, v160, v160
	v_mul_f32_e32 v160, v192, v192
	v_fmac_f32_e32 v160, v183, v183
	v_cvt_pk_bf16_f32 v185, v183, v192
	v_add_f32_e32 v160, v161, v160
	v_mul_f32_e32 v161, v194, v194
	v_mul_f32_e32 v183, v196, v196
	v_fmac_f32_e32 v161, v193, v193
	v_fmac_f32_e32 v183, v195, v195
	v_add_f32_e32 v161, v161, v183
	v_add_f32_e32 v160, v160, v161
	s_waitcnt vmcnt(2)
	v_lshlrev_b32_e32 v161, 16, v188
	v_and_b32_e32 v183, 0xffff0000, v188
	v_lshlrev_b32_e32 v188, 16, v189
	v_add_f32_e32 v192, v88, v188
	v_and_b32_e32 v188, 0xffff0000, v189
	v_cvt_pk_bf16_f32 v186, v193, v194
	v_add_f32_e32 v193, v89, v188
	v_lshlrev_b32_e32 v188, 16, v190
	v_add_f32_e32 v194, v82, v188
	v_and_b32_e32 v188, 0xffff0000, v190
	v_cvt_pk_bf16_f32 v187, v195, v196
	v_add_f32_e32 v195, v83, v188
	v_lshlrev_b32_e32 v188, 16, v191
	v_add_f32_e32 v183, v87, v183
	v_add_f32_e32 v196, v84, v188
	v_and_b32_e32 v188, 0xffff0000, v191
	v_add_f32_e32 v161, v86, v161
	v_add_f32_e32 v197, v85, v188
	v_cvt_pk_bf16_f32 v188, v161, v183
	v_mul_f32_e32 v183, v183, v183
	v_fmac_f32_e32 v183, v161, v161
	v_mul_f32_e32 v161, v193, v193
	v_fmac_f32_e32 v161, v192, v192
	v_cvt_pk_bf16_f32 v189, v192, v193
	v_add_f32_e32 v161, v183, v161
	v_mul_f32_e32 v183, v195, v195
	v_mul_f32_e32 v192, v197, v197
	v_fmac_f32_e32 v183, v194, v194
	v_fmac_f32_e32 v192, v196, v196
	v_cvt_pk_bf16_f32 v190, v194, v195
	v_add_f32_e32 v183, v183, v192
	v_cndmask_b32_e64 v193, v188, v184, s[36:37]
	v_mov_b32_e32 v194, v115
	v_add_f32_e32 v161, v161, v183
	v_cndmask_b32_e64 v192, v189, v185, s[36:37]
	v_mov_b32_dpp v194, v193 quad_perm:[1,0,3,2] row_mask:0xf bank_mask:0xf
	v_mov_b32_e32 v193, v115
	v_cvt_pk_bf16_f32 v191, v196, v197
	v_add_f32_e32 v183, v160, v161
	v_cndmask_b32_e64 v160, v191, v187, s[36:37]
	v_cndmask_b32_e64 v161, v190, v186, s[36:37]
	v_mov_b32_dpp v193, v192 quad_perm:[1,0,3,2] row_mask:0xf bank_mask:0xf
	v_mov_b32_e32 v192, v115
	v_mov_b32_e32 v195, v115
	v_cndmask_b32_e64 v184, v184, v194, s[36:37]
	v_mov_b32_dpp v192, v161 quad_perm:[1,0,3,2] row_mask:0xf bank_mask:0xf
	v_mov_b32_dpp v195, v160 quad_perm:[1,0,3,2] row_mask:0xf bank_mask:0xf
	v_cndmask_b32_e64 v185, v185, v193, s[36:37]
	v_cndmask_b32_e64 v186, v186, v192, s[36:37]
	v_cndmask_b32_e64 v187, v187, v195, s[36:37]
	v_lshl_add_u64 v[160:161], v[148:149], 1, s[24:25]
	global_store_dwordx4 v[160:161], v[184:187], off nt
	v_lshl_add_u64 v[160:161], v[150:151], 1, s[24:25]
	s_nop 0
	v_cndmask_b32_e64 v184, v194, v188, s[36:37]
	v_cndmask_b32_e64 v185, v193, v189, s[36:37]
	v_cndmask_b32_e64 v186, v192, v190, s[36:37]
	v_cndmask_b32_e64 v187, v195, v191, s[36:37]
	global_store_dwordx4 v[160:161], v[184:187], off nt
	ds_bpermute_b32 v160, v181, v183
	s_waitcnt lgkmcnt(0)
	v_add_f32_e32 v183, v183, v160
	ds_bpermute_b32 v184, v182, v183
	s_and_saveexec_b64 s[24:25], s[38:39]
	s_cbranch_execz .LBB0_1278
	v_or_b32_e32 v160, 32, v176
	v_ashrrev_i32_e32 v161, 31, v160
	v_lshlrev_b64 v[160:161], 7, v[160:161]
	v_lshl_add_u64 v[160:161], s[6:7], 0, v[160:161]
	v_lshl_add_u64 v[160:161], s[22:23], 2, v[160:161]
	s_lshl_b32 s4, s53, 2
	s_waitcnt lgkmcnt(0)
	v_add_f32_e32 v183, v183, v184
	v_lshl_add_u64 v[160:161], v[160:161], 0, s[4:5]
	global_store_dword v[160:161], v183, off nt

.LBB0_1280:
	s_or_b64 exec, exec, s[24:25]
	v_add_co_u32_e32 v132, vcc, 0x80000, v174
	s_add_u32 s24, s20, 0x80000
	s_waitcnt lgkmcnt(0)
	v_addc_co_u32_e32 v133, vcc, 0, v175, vcc
	global_load_dwordx4 v[184:187], v[132:133], off nt
	global_load_dwordx4 v[188:191], v[132:133], off offset:64 nt
	v_add_co_u32_e32 v132, vcc, 0x90000, v174
	s_addc_u32 s25, s21, 0
	s_nop 0
	v_addc_co_u32_e32 v133, vcc, 0, v175, vcc
	global_load_dwordx4 v[136:139], v[132:133], off nt
	s_nop 0
	global_load_dwordx4 v[132:135], v[132:133], off offset:64 nt
	s_waitcnt vmcnt(3)
	v_lshlrev_b32_e32 v160, 16, v184
	v_and_b32_e32 v161, 0xffff0000, v184
	v_and_b32_e32 v184, 0xffff0000, v185
	v_add_f32_e32 v192, v65, v184
	v_lshlrev_b32_e32 v184, 16, v186
	v_add_f32_e32 v193, v58, v184
	v_and_b32_e32 v184, 0xffff0000, v186
	v_add_f32_e32 v194, v59, v184
	v_lshlrev_b32_e32 v184, 16, v187
	v_add_f32_e32 v161, v63, v161
	v_add_f32_e32 v195, v60, v184
	v_and_b32_e32 v184, 0xffff0000, v187
	v_add_f32_e32 v160, v62, v160
	v_lshlrev_b32_e32 v183, 16, v185
	v_add_f32_e32 v196, v61, v184
	v_cvt_pk_bf16_f32 v184, v160, v161
	v_mul_f32_e32 v161, v161, v161
	v_add_f32_e32 v183, v64, v183
	v_fmac_f32_e32 v161, v160, v160
	v_mul_f32_e32 v160, v192, v192
	v_fmac_f32_e32 v160, v183, v183
	v_cvt_pk_bf16_f32 v185, v183, v192
	v_add_f32_e32 v160, v161, v160
	v_mul_f32_e32 v161, v194, v194
	v_mul_f32_e32 v183, v196, v196
	v_fmac_f32_e32 v161, v193, v193
	v_fmac_f32_e32 v183, v195, v195
	v_add_f32_e32 v161, v161, v183
	v_add_f32_e32 v160, v160, v161
	s_waitcnt vmcnt(2)
	v_lshlrev_b32_e32 v161, 16, v188
	v_and_b32_e32 v183, 0xffff0000, v188
	v_lshlrev_b32_e32 v188, 16, v189
	v_add_f32_e32 v192, v56, v188
	v_and_b32_e32 v188, 0xffff0000, v189
	v_cvt_pk_bf16_f32 v186, v193, v194
	v_add_f32_e32 v193, v57, v188
	v_lshlrev_b32_e32 v188, 16, v190
	v_add_f32_e32 v194, v50, v188
	v_and_b32_e32 v188, 0xffff0000, v190
	v_cvt_pk_bf16_f32 v187, v195, v196
	v_add_f32_e32 v195, v51, v188
	v_lshlrev_b32_e32 v188, 16, v191
	v_add_f32_e32 v183, v55, v183
	v_add_f32_e32 v196, v52, v188
	v_and_b32_e32 v188, 0xffff0000, v191
	v_add_f32_e32 v161, v54, v161
	v_add_f32_e32 v197, v53, v188
	v_cvt_pk_bf16_f32 v188, v161, v183
	v_mul_f32_e32 v183, v183, v183
	v_fmac_f32_e32 v183, v161, v161
	v_mul_f32_e32 v161, v193, v193
	v_fmac_f32_e32 v161, v192, v192
	v_cvt_pk_bf16_f32 v189, v192, v193
	v_add_f32_e32 v161, v183, v161
	v_mul_f32_e32 v183, v195, v195
	v_mul_f32_e32 v192, v197, v197
	v_fmac_f32_e32 v183, v194, v194
	v_fmac_f32_e32 v192, v196, v196
	v_cvt_pk_bf16_f32 v190, v194, v195
	v_add_f32_e32 v183, v183, v192
	v_cndmask_b32_e64 v193, v188, v184, s[36:37]
	v_mov_b32_e32 v194, v115
	v_add_f32_e32 v161, v161, v183
	v_cndmask_b32_e64 v192, v189, v185, s[36:37]
	v_mov_b32_dpp v194, v193 quad_perm:[1,0,3,2] row_mask:0xf bank_mask:0xf
	v_mov_b32_e32 v193, v115
	v_cvt_pk_bf16_f32 v191, v196, v197
	v_add_f32_e32 v183, v160, v161
	v_cndmask_b32_e64 v160, v191, v187, s[36:37]
	v_cndmask_b32_e64 v161, v190, v186, s[36:37]
	v_mov_b32_dpp v193, v192 quad_perm:[1,0,3,2] row_mask:0xf bank_mask:0xf
	v_mov_b32_e32 v192, v115
	v_mov_b32_e32 v195, v115
	v_cndmask_b32_e64 v184, v184, v194, s[36:37]
	v_mov_b32_dpp v192, v161 quad_perm:[1,0,3,2] row_mask:0xf bank_mask:0xf
	v_mov_b32_dpp v195, v160 quad_perm:[1,0,3,2] row_mask:0xf bank_mask:0xf
	v_cndmask_b32_e64 v185, v185, v193, s[36:37]
	v_cndmask_b32_e64 v186, v186, v192, s[36:37]
	v_cndmask_b32_e64 v187, v187, v195, s[36:37]
	v_lshl_add_u64 v[160:161], v[148:149], 1, s[24:25]
	global_store_dwordx4 v[160:161], v[184:187], off nt
	v_lshl_add_u64 v[160:161], v[150:151], 1, s[24:25]
	s_nop 0
	v_cndmask_b32_e64 v184, v194, v188, s[36:37]
	v_cndmask_b32_e64 v185, v193, v189, s[36:37]
	v_cndmask_b32_e64 v186, v192, v190, s[36:37]
	v_cndmask_b32_e64 v187, v195, v191, s[36:37]
	global_store_dwordx4 v[160:161], v[184:187], off nt
	ds_bpermute_b32 v160, v181, v183
	s_waitcnt lgkmcnt(0)
	v_add_f32_e32 v183, v183, v160
	ds_bpermute_b32 v184, v182, v183
	s_and_saveexec_b64 s[24:25], s[38:39]
	s_cbranch_execz .LBB0_1282
	v_lshlrev_b64 v[160:161], 7, v[176:177]
	v_lshl_add_u64 v[160:161], s[6:7], 0, v[160:161]
	v_lshl_add_u64 v[160:161], s[22:23], 2, v[160:161]
	s_lshl_b32 s4, s53, 2
	v_lshl_add_u64 v[160:161], v[160:161], 0, s[4:5]
	v_add_co_u32_e32 v160, vcc, 0x4000, v160
	s_waitcnt lgkmcnt(0)
	v_add_f32_e32 v183, v183, v184
	v_addc_co_u32_e32 v161, vcc, 0, v161, vcc
	global_store_dword v[160:161], v183, off nt

.LBB0_1284:
	s_or_b64 exec, exec, s[24:25]
	v_add_co_u32_e32 v132, vcc, 0xa0000, v174
	s_add_u32 s24, s20, 0xa0000
	s_waitcnt lgkmcnt(0)
	v_addc_co_u32_e32 v133, vcc, 0, v175, vcc
	global_load_dwordx4 v[184:187], v[132:133], off nt
	global_load_dwordx4 v[188:191], v[132:133], off offset:64 nt
	v_add_co_u32_e32 v132, vcc, 0xb0000, v174
	s_addc_u32 s25, s21, 0
	s_nop 0
	v_addc_co_u32_e32 v133, vcc, 0, v175, vcc
	global_load_dwordx4 v[136:139], v[132:133], off nt
	s_nop 0
	global_load_dwordx4 v[132:135], v[132:133], off offset:64 nt
	s_waitcnt vmcnt(3)
	v_lshlrev_b32_e32 v160, 16, v184
	v_and_b32_e32 v161, 0xffff0000, v184
	v_and_b32_e32 v184, 0xffff0000, v185
	v_add_f32_e32 v192, v33, v184
	v_lshlrev_b32_e32 v184, 16, v186
	v_add_f32_e32 v193, v26, v184
	v_and_b32_e32 v184, 0xffff0000, v186
	v_add_f32_e32 v194, v27, v184
	v_lshlrev_b32_e32 v184, 16, v187
	v_add_f32_e32 v161, v31, v161
	v_add_f32_e32 v195, v28, v184
	v_and_b32_e32 v184, 0xffff0000, v187
	v_add_f32_e32 v160, v30, v160
	v_lshlrev_b32_e32 v183, 16, v185
	v_add_f32_e32 v196, v29, v184
	v_cvt_pk_bf16_f32 v184, v160, v161
	v_mul_f32_e32 v161, v161, v161
	v_add_f32_e32 v183, v32, v183
	v_fmac_f32_e32 v161, v160, v160
	v_mul_f32_e32 v160, v192, v192
	v_fmac_f32_e32 v160, v183, v183
	v_cvt_pk_bf16_f32 v185, v183, v192
	v_add_f32_e32 v160, v161, v160
	v_mul_f32_e32 v161, v194, v194
	v_mul_f32_e32 v183, v196, v196
	v_fmac_f32_e32 v161, v193, v193
	v_fmac_f32_e32 v183, v195, v195
	v_add_f32_e32 v161, v161, v183
	v_add_f32_e32 v160, v160, v161
	s_waitcnt vmcnt(2)
	v_lshlrev_b32_e32 v161, 16, v188
	v_and_b32_e32 v183, 0xffff0000, v188
	v_lshlrev_b32_e32 v188, 16, v189
	v_add_f32_e32 v192, v24, v188
	v_and_b32_e32 v188, 0xffff0000, v189
	v_cvt_pk_bf16_f32 v186, v193, v194
	v_add_f32_e32 v193, v25, v188
	v_lshlrev_b32_e32 v188, 16, v190
	v_add_f32_e32 v194, v18, v188
	v_and_b32_e32 v188, 0xffff0000, v190
	v_cvt_pk_bf16_f32 v187, v195, v196
	v_add_f32_e32 v195, v19, v188
	v_lshlrev_b32_e32 v188, 16, v191
	v_add_f32_e32 v183, v23, v183
	v_add_f32_e32 v196, v20, v188
	v_and_b32_e32 v188, 0xffff0000, v191
	v_add_f32_e32 v161, v22, v161
	v_add_f32_e32 v197, v21, v188
	v_cvt_pk_bf16_f32 v188, v161, v183
	v_mul_f32_e32 v183, v183, v183
	v_fmac_f32_e32 v183, v161, v161
	v_mul_f32_e32 v161, v193, v193
	v_fmac_f32_e32 v161, v192, v192
	v_cvt_pk_bf16_f32 v189, v192, v193
	v_add_f32_e32 v161, v183, v161
	v_mul_f32_e32 v183, v195, v195
	v_mul_f32_e32 v192, v197, v197
	v_fmac_f32_e32 v183, v194, v194
	v_fmac_f32_e32 v192, v196, v196
	v_cvt_pk_bf16_f32 v190, v194, v195
	v_add_f32_e32 v183, v183, v192
	v_cndmask_b32_e64 v193, v188, v184, s[36:37]
	v_mov_b32_e32 v194, v115
	v_add_f32_e32 v161, v161, v183
	v_cndmask_b32_e64 v192, v189, v185, s[36:37]
	v_mov_b32_dpp v194, v193 quad_perm:[1,0,3,2] row_mask:0xf bank_mask:0xf
	v_mov_b32_e32 v193, v115
	v_cvt_pk_bf16_f32 v191, v196, v197
	v_add_f32_e32 v183, v160, v161
	v_cndmask_b32_e64 v160, v191, v187, s[36:37]
	v_cndmask_b32_e64 v161, v190, v186, s[36:37]
	v_mov_b32_dpp v193, v192 quad_perm:[1,0,3,2] row_mask:0xf bank_mask:0xf
	v_mov_b32_e32 v192, v115
	v_mov_b32_e32 v195, v115
	v_cndmask_b32_e64 v184, v184, v194, s[36:37]
	v_mov_b32_dpp v192, v161 quad_perm:[1,0,3,2] row_mask:0xf bank_mask:0xf
	v_mov_b32_dpp v195, v160 quad_perm:[1,0,3,2] row_mask:0xf bank_mask:0xf
	v_cndmask_b32_e64 v185, v185, v193, s[36:37]
	v_cndmask_b32_e64 v186, v186, v192, s[36:37]
	v_cndmask_b32_e64 v187, v187, v195, s[36:37]
	v_lshl_add_u64 v[160:161], v[148:149], 1, s[24:25]
	global_store_dwordx4 v[160:161], v[184:187], off nt
	v_lshl_add_u64 v[160:161], v[150:151], 1, s[24:25]
	s_nop 0
	v_cndmask_b32_e64 v184, v194, v188, s[36:37]
	v_cndmask_b32_e64 v185, v193, v189, s[36:37]
	v_cndmask_b32_e64 v186, v192, v190, s[36:37]
	v_cndmask_b32_e64 v187, v195, v191, s[36:37]
	global_store_dwordx4 v[160:161], v[184:187], off nt
	ds_bpermute_b32 v160, v181, v183
	s_waitcnt lgkmcnt(0)
	v_add_f32_e32 v183, v183, v160
	ds_bpermute_b32 v184, v182, v183
	s_and_saveexec_b64 s[24:25], s[38:39]
	s_cbranch_execz .LBB0_1286
	v_lshlrev_b64 v[160:161], 7, v[176:177]
	v_lshl_add_u64 v[160:161], s[6:7], 0, v[160:161]
	v_lshl_add_u64 v[160:161], s[22:23], 2, v[160:161]
	s_lshl_b32 s4, s53, 2
	v_lshl_add_u64 v[160:161], v[160:161], 0, s[4:5]
	v_add_co_u32_e32 v160, vcc, 0x5000, v160
	s_waitcnt lgkmcnt(0)
	v_add_f32_e32 v183, v183, v184
	v_addc_co_u32_e32 v161, vcc, 0, v161, vcc
	global_store_dword v[160:161], v183, off nt

.LBB0_1289:
	s_waitcnt lgkmcnt(0)
	global_load_dwordx4 v[132:135], v[174:175], off nt
	s_lshl_b64 s[18:19], s[18:19], 2
	s_add_u32 s18, s90, s18
	s_addc_u32 s19, s91, s19
	v_lshl_add_u64 v[136:137], v[146:147], 2, s[18:19]
	s_waitcnt vmcnt(0)
	v_lshlrev_b32_e32 v138, 16, v132
	v_and_b32_e32 v139, 0xffff0000, v132
	v_lshlrev_b32_e32 v132, 16, v133
	v_and_b32_e32 v133, 0xffff0000, v133
	v_pk_add_f32 v[130:131], v[130:131], v[132:133]
	v_lshlrev_b32_e32 v132, 16, v134
	v_and_b32_e32 v133, 0xffff0000, v134
	v_pk_add_f32 v[128:129], v[128:129], v[138:139]
	v_pk_add_f32 v[124:125], v[124:125], v[132:133]
	v_lshlrev_b32_e32 v132, 16, v135
	v_and_b32_e32 v133, 0xffff0000, v135
	v_pk_add_f32 v[126:127], v[126:127], v[132:133]
	global_store_dwordx4 v[136:137], v[128:131], off nt
	global_store_dwordx4 v[136:137], v[124:127], off offset:16 nt
	global_load_dwordx4 v[124:127], v[174:175], off offset:64 nt
	s_waitcnt vmcnt(0)
	v_lshlrev_b32_e32 v128, 16, v124
	v_and_b32_e32 v129, 0xffff0000, v124
	v_lshlrev_b32_e32 v124, 16, v125
	v_and_b32_e32 v125, 0xffff0000, v125
	v_pk_add_f32 v[122:123], v[122:123], v[124:125]
	v_lshlrev_b32_e32 v124, 16, v126
	v_and_b32_e32 v125, 0xffff0000, v126
	v_pk_add_f32 v[120:121], v[120:121], v[128:129]
	v_pk_add_f32 v[116:117], v[116:117], v[124:125]
	v_lshlrev_b32_e32 v124, 16, v127
	v_and_b32_e32 v125, 0xffff0000, v127
	v_pk_add_f32 v[118:119], v[118:119], v[124:125]
	global_store_dwordx4 v[136:137], v[120:123], off offset:128 nt
	global_store_dwordx4 v[136:137], v[116:119], off offset:144 nt
	s_nop 0
	v_lshl_add_u64 v[120:121], v[152:153], 1, s[16:17]
	global_load_dwordx4 v[116:119], v[120:121], off nt
	v_lshl_add_u64 v[122:123], v[152:153], 2, s[18:19]
	s_waitcnt vmcnt(0)
	v_lshlrev_b32_e32 v124, 16, v116
	v_and_b32_e32 v125, 0xffff0000, v116
	v_lshlrev_b32_e32 v116, 16, v117
	v_and_b32_e32 v117, 0xffff0000, v117
	v_pk_add_f32 v[112:113], v[112:113], v[116:117]
	v_lshlrev_b32_e32 v116, 16, v118
	v_and_b32_e32 v117, 0xffff0000, v118
	v_pk_add_f32 v[110:111], v[110:111], v[124:125]
	v_pk_add_f32 v[106:107], v[106:107], v[116:117]
	v_lshlrev_b32_e32 v116, 16, v119
	v_and_b32_e32 v117, 0xffff0000, v119
	v_pk_add_f32 v[108:109], v[108:109], v[116:117]
	global_store_dwordx4 v[122:123], v[110:113], off nt
	global_store_dwordx4 v[122:123], v[106:109], off offset:16 nt
	global_load_dwordx4 v[106:109], v[120:121], off offset:64 nt
	s_waitcnt vmcnt(0)
	v_lshlrev_b32_e32 v110, 16, v106
	v_and_b32_e32 v111, 0xffff0000, v106
	v_lshlrev_b32_e32 v106, 16, v107
	v_and_b32_e32 v107, 0xffff0000, v107
	v_pk_add_f32 v[104:105], v[104:105], v[106:107]
	v_lshlrev_b32_e32 v106, 16, v108
	v_and_b32_e32 v107, 0xffff0000, v108
	v_pk_add_f32 v[102:103], v[102:103], v[110:111]
	v_pk_add_f32 v[98:99], v[98:99], v[106:107]
	v_lshlrev_b32_e32 v106, 16, v109
	v_and_b32_e32 v107, 0xffff0000, v109
	v_pk_add_f32 v[100:101], v[100:101], v[106:107]
	global_store_dwordx4 v[122:123], v[102:105], off offset:128 nt
	global_store_dwordx4 v[122:123], v[98:101], off offset:144 nt
	s_nop 0
	v_lshl_add_u64 v[102:103], v[154:155], 1, s[16:17]
	global_load_dwordx4 v[98:101], v[102:103], off nt
	v_lshl_add_u64 v[104:105], v[154:155], 2, s[18:19]
	s_waitcnt vmcnt(0)
	v_lshlrev_b32_e32 v106, 16, v98
	v_and_b32_e32 v107, 0xffff0000, v98
	v_lshlrev_b32_e32 v98, 16, v99
	v_and_b32_e32 v99, 0xffff0000, v99
	v_pk_add_f32 v[96:97], v[96:97], v[98:99]
	v_lshlrev_b32_e32 v98, 16, v100
	v_and_b32_e32 v99, 0xffff0000, v100
	v_pk_add_f32 v[94:95], v[94:95], v[106:107]
	v_pk_add_f32 v[90:91], v[90:91], v[98:99]
	v_lshlrev_b32_e32 v98, 16, v101
	v_and_b32_e32 v99, 0xffff0000, v101
	v_pk_add_f32 v[92:93], v[92:93], v[98:99]
	global_store_dwordx4 v[104:105], v[94:97], off nt
	global_store_dwordx4 v[104:105], v[90:93], off offset:16 nt
	global_load_dwordx4 v[90:93], v[102:103], off offset:64 nt
	s_waitcnt vmcnt(0)
	v_lshlrev_b32_e32 v94, 16, v90
	v_and_b32_e32 v95, 0xffff0000, v90
	v_lshlrev_b32_e32 v90, 16, v91
	v_and_b32_e32 v91, 0xffff0000, v91
	v_pk_add_f32 v[88:89], v[88:89], v[90:91]
	v_lshlrev_b32_e32 v90, 16, v92
	v_and_b32_e32 v91, 0xffff0000, v92
	v_pk_add_f32 v[86:87], v[86:87], v[94:95]
	v_pk_add_f32 v[82:83], v[82:83], v[90:91]
	v_lshlrev_b32_e32 v90, 16, v93
	v_and_b32_e32 v91, 0xffff0000, v93
	v_pk_add_f32 v[84:85], v[84:85], v[90:91]
	global_store_dwordx4 v[104:105], v[86:89], off offset:128 nt
	global_store_dwordx4 v[104:105], v[82:85], off offset:144 nt
	s_nop 0
	v_lshl_add_u64 v[86:87], v[156:157], 1, s[16:17]
	global_load_dwordx4 v[82:85], v[86:87], off nt
	v_lshl_add_u64 v[88:89], v[156:157], 2, s[18:19]
	s_waitcnt vmcnt(0)
	v_lshlrev_b32_e32 v90, 16, v82
	v_and_b32_e32 v91, 0xffff0000, v82
	v_lshlrev_b32_e32 v82, 16, v83
	v_and_b32_e32 v83, 0xffff0000, v83
	v_pk_add_f32 v[80:81], v[80:81], v[82:83]
	v_lshlrev_b32_e32 v82, 16, v84
	v_and_b32_e32 v83, 0xffff0000, v84
	v_pk_add_f32 v[78:79], v[78:79], v[90:91]
	v_pk_add_f32 v[74:75], v[74:75], v[82:83]
	v_lshlrev_b32_e32 v82, 16, v85
	v_and_b32_e32 v83, 0xffff0000, v85
	v_pk_add_f32 v[76:77], v[76:77], v[82:83]
	global_store_dwordx4 v[88:89], v[78:81], off nt
	global_store_dwordx4 v[88:89], v[74:77], off offset:16 nt
	global_load_dwordx4 v[74:77], v[86:87], off offset:64 nt
	s_waitcnt vmcnt(0)
	v_lshlrev_b32_e32 v78, 16, v74
	v_and_b32_e32 v79, 0xffff0000, v74
	v_lshlrev_b32_e32 v74, 16, v75
	v_and_b32_e32 v75, 0xffff0000, v75
	v_pk_add_f32 v[72:73], v[72:73], v[74:75]
	v_lshlrev_b32_e32 v74, 16, v76
	v_and_b32_e32 v75, 0xffff0000, v76
	v_pk_add_f32 v[70:71], v[70:71], v[78:79]
	v_pk_add_f32 v[66:67], v[66:67], v[74:75]
	v_lshlrev_b32_e32 v74, 16, v77
	v_and_b32_e32 v75, 0xffff0000, v77
	v_pk_add_f32 v[68:69], v[68:69], v[74:75]
	global_store_dwordx4 v[88:89], v[70:73], off offset:128 nt
	global_store_dwordx4 v[88:89], v[66:69], off offset:144 nt
	s_nop 0
	v_lshl_add_u64 v[70:71], v[158:159], 1, s[16:17]
	global_load_dwordx4 v[66:69], v[70:71], off nt
	v_lshl_add_u64 v[72:73], v[158:159], 2, s[18:19]
	s_waitcnt vmcnt(0)
	v_lshlrev_b32_e32 v74, 16, v66
	v_and_b32_e32 v75, 0xffff0000, v66
	v_lshlrev_b32_e32 v66, 16, v67
	v_and_b32_e32 v67, 0xffff0000, v67
	v_pk_add_f32 v[64:65], v[64:65], v[66:67]
	v_lshlrev_b32_e32 v66, 16, v68
	v_and_b32_e32 v67, 0xffff0000, v68
	v_pk_add_f32 v[62:63], v[62:63], v[74:75]
	v_pk_add_f32 v[58:59], v[58:59], v[66:67]
	v_lshlrev_b32_e32 v66, 16, v69
	v_and_b32_e32 v67, 0xffff0000, v69
	v_pk_add_f32 v[60:61], v[60:61], v[66:67]
	global_store_dwordx4 v[72:73], v[62:65], off nt
	global_store_dwordx4 v[72:73], v[58:61], off offset:16 nt
	global_load_dwordx4 v[58:61], v[70:71], off offset:64 nt
	s_waitcnt vmcnt(0)
	v_lshlrev_b32_e32 v62, 16, v58
	v_and_b32_e32 v63, 0xffff0000, v58
	v_lshlrev_b32_e32 v58, 16, v59
	v_and_b32_e32 v59, 0xffff0000, v59
	v_pk_add_f32 v[56:57], v[56:57], v[58:59]
	v_lshlrev_b32_e32 v58, 16, v60
	v_and_b32_e32 v59, 0xffff0000, v60
	v_pk_add_f32 v[54:55], v[54:55], v[62:63]
	v_pk_add_f32 v[50:51], v[50:51], v[58:59]
	v_lshlrev_b32_e32 v58, 16, v61
	v_and_b32_e32 v59, 0xffff0000, v61
	v_pk_add_f32 v[52:53], v[52:53], v[58:59]
	global_store_dwordx4 v[72:73], v[54:57], off offset:128 nt
	global_store_dwordx4 v[72:73], v[50:53], off offset:144 nt
	s_nop 0
	v_lshl_add_u64 v[54:55], v[164:165], 1, s[16:17]
	global_load_dwordx4 v[50:53], v[54:55], off nt
	v_lshl_add_u64 v[56:57], v[164:165], 2, s[18:19]
	s_waitcnt vmcnt(0)
	v_lshlrev_b32_e32 v58, 16, v50
	v_and_b32_e32 v59, 0xffff0000, v50
	v_lshlrev_b32_e32 v50, 16, v51
	v_and_b32_e32 v51, 0xffff0000, v51
	v_pk_add_f32 v[48:49], v[48:49], v[50:51]
	v_lshlrev_b32_e32 v50, 16, v52
	v_and_b32_e32 v51, 0xffff0000, v52
	v_pk_add_f32 v[46:47], v[46:47], v[58:59]
	v_pk_add_f32 v[42:43], v[42:43], v[50:51]
	v_lshlrev_b32_e32 v50, 16, v53
	v_and_b32_e32 v51, 0xffff0000, v53
	v_pk_add_f32 v[44:45], v[44:45], v[50:51]
	global_store_dwordx4 v[56:57], v[46:49], off nt
	global_store_dwordx4 v[56:57], v[42:45], off offset:16 nt
	global_load_dwordx4 v[42:45], v[54:55], off offset:64 nt
	s_waitcnt vmcnt(0)
	v_lshlrev_b32_e32 v46, 16, v42
	v_and_b32_e32 v47, 0xffff0000, v42
	v_lshlrev_b32_e32 v42, 16, v43
	v_and_b32_e32 v43, 0xffff0000, v43
	v_pk_add_f32 v[40:41], v[40:41], v[42:43]
	v_lshlrev_b32_e32 v42, 16, v44
	v_and_b32_e32 v43, 0xffff0000, v44
	v_pk_add_f32 v[38:39], v[38:39], v[46:47]
	v_pk_add_f32 v[34:35], v[34:35], v[42:43]
	v_lshlrev_b32_e32 v42, 16, v45
	v_and_b32_e32 v43, 0xffff0000, v45
	v_pk_add_f32 v[36:37], v[36:37], v[42:43]
	global_store_dwordx4 v[56:57], v[38:41], off offset:128 nt
	global_store_dwordx4 v[56:57], v[34:37], off offset:144 nt
	s_nop 0
	v_lshl_add_u64 v[38:39], v[166:167], 1, s[16:17]
	global_load_dwordx4 v[34:37], v[38:39], off nt
	v_lshl_add_u64 v[40:41], v[166:167], 2, s[18:19]
	s_waitcnt vmcnt(0)
	v_lshlrev_b32_e32 v42, 16, v34
	v_and_b32_e32 v43, 0xffff0000, v34
	v_lshlrev_b32_e32 v34, 16, v35
	v_and_b32_e32 v35, 0xffff0000, v35
	v_pk_add_f32 v[32:33], v[32:33], v[34:35]
	v_lshlrev_b32_e32 v34, 16, v36
	v_and_b32_e32 v35, 0xffff0000, v36
	v_pk_add_f32 v[30:31], v[30:31], v[42:43]
	v_pk_add_f32 v[26:27], v[26:27], v[34:35]
	v_lshlrev_b32_e32 v34, 16, v37
	v_and_b32_e32 v35, 0xffff0000, v37
	v_pk_add_f32 v[28:29], v[28:29], v[34:35]
	global_store_dwordx4 v[40:41], v[30:33], off nt
	global_store_dwordx4 v[40:41], v[26:29], off offset:16 nt
	global_load_dwordx4 v[26:29], v[38:39], off offset:64 nt
	s_waitcnt vmcnt(0)
	v_lshlrev_b32_e32 v30, 16, v26
	v_and_b32_e32 v31, 0xffff0000, v26
	v_lshlrev_b32_e32 v26, 16, v27
	v_and_b32_e32 v27, 0xffff0000, v27
	v_pk_add_f32 v[24:25], v[24:25], v[26:27]
	v_lshlrev_b32_e32 v26, 16, v28
	v_and_b32_e32 v27, 0xffff0000, v28
	v_pk_add_f32 v[22:23], v[22:23], v[30:31]
	v_pk_add_f32 v[18:19], v[18:19], v[26:27]
	v_lshlrev_b32_e32 v26, 16, v29
	v_and_b32_e32 v27, 0xffff0000, v29
	v_pk_add_f32 v[20:21], v[20:21], v[26:27]
	global_store_dwordx4 v[40:41], v[22:25], off offset:128 nt
	global_store_dwordx4 v[40:41], v[18:21], off offset:144 nt
	s_nop 0
	v_lshl_add_u64 v[22:23], v[168:169], 1, s[16:17]
	global_load_dwordx4 v[18:21], v[22:23], off nt
	v_lshl_add_u64 v[24:25], v[168:169], 2, s[18:19]
	s_waitcnt vmcnt(0)
	v_lshlrev_b32_e32 v26, 16, v18
	v_and_b32_e32 v27, 0xffff0000, v18
	v_lshlrev_b32_e32 v18, 16, v19
	v_and_b32_e32 v19, 0xffff0000, v19
	v_pk_add_f32 v[16:17], v[16:17], v[18:19]
	v_lshlrev_b32_e32 v18, 16, v20
	v_and_b32_e32 v19, 0xffff0000, v20
	v_pk_add_f32 v[14:15], v[14:15], v[26:27]
	v_pk_add_f32 v[10:11], v[10:11], v[18:19]
	v_lshlrev_b32_e32 v18, 16, v21
	v_and_b32_e32 v19, 0xffff0000, v21
	v_pk_add_f32 v[12:13], v[12:13], v[18:19]
	global_store_dwordx4 v[24:25], v[14:17], off nt
	global_store_dwordx4 v[24:25], v[10:13], off offset:16 nt
	global_load_dwordx4 v[10:13], v[22:23], off offset:64 nt
	s_waitcnt vmcnt(0)
	v_lshlrev_b32_e32 v14, 16, v10
	v_and_b32_e32 v15, 0xffff0000, v10
	v_lshlrev_b32_e32 v10, 16, v11
	v_and_b32_e32 v11, 0xffff0000, v11
	v_pk_add_f32 v[8:9], v[8:9], v[10:11]
	v_lshlrev_b32_e32 v10, 16, v12
	v_and_b32_e32 v11, 0xffff0000, v12
	v_pk_add_f32 v[6:7], v[6:7], v[14:15]
	v_pk_add_f32 v[2:3], v[2:3], v[10:11]
	v_lshlrev_b32_e32 v10, 16, v13
	v_and_b32_e32 v11, 0xffff0000, v13
	v_pk_add_f32 v[4:5], v[4:5], v[10:11]
	global_store_dwordx4 v[24:25], v[6:9], off offset:128 nt
	global_store_dwordx4 v[24:25], v[2:5], off offset:144 nt
	s_and_b64 vcc, exec, s[40:41]
	s_mov_b64 s[16:17], -1
	s_cbranch_vccnz .LBB0_1258
